# hand-written P5 LayerNorm (gamma/beta in registers, row loads up front, no waits behind stores) on top of tilebyte + P0 fast path
# baseline (speedup 1.0000x reference)
; __global__ void __launch_bounds__(512, 2) hybrid_fwd(Args a) {
;     ...
;         const int xcd = bx & 7, cu_in_x = bx >> 3, per_x = G >> 3;
;         const int gw = (G % 8 == 0) ? (cu_in_x * 8 + wave) : (bx * 8 + wave), NGW = (G % 8 == 0) ? per_x * 8 : G * 8;
;         const int row_base = (G % 8 == 0) ? xcd * (M / 8) : 0, row_cnt = (G % 8 == 0) ? (M / 8) : M;
;         typedef _Float16 h8 __attribute__((ext_vector_type(8)));
;         for (int tl = gw; tl < row_cnt; tl += 8 * NGW) {
;             int tr[8]; f32x2 pr[8]; h8 zz[8][4];
; #pragma unroll
;             for (int u = 0; u < 8; ++u) { tr[u] = (tl + u * NGW < row_cnt) ? row_base + tl + u * NGW : row_base + tl;
;                 pr[u] = (lane < 32) ? STATS[(size_t)tr[u] * 32 + lane] : (f32x2){0.f, 0.f};
; #pragma unroll
;                 for (int j = 0; j < 4; ++j) zz[u][j] = *(const h8*)(Z16 + (size_t)tr[u] * D + 512 * j + 8 * lane); }
; #pragma unroll
;             for (int u = 0; u < 8; ++u) {
;                 float s0 = pr[u].x, q0 = pr[u].y;
; #pragma unroll
;                 for (int o = 1; o < 64; o <<= 1) { s0 += __shfl_xor(s0, o); q0 += __shfl_xor(q0, o); }
.LBB0_525:
	s_or_b64 exec, exec, s[4:5]
	s_and_b32 s2, s2, -8
	v_readlane_b32 s3, v242, 0
	s_add_i32 s2, s3, s2
	v_readlane_b32 s4, v242, 1
	v_mov_b32_e32 v1, s2
	s_nop 0
	v_mov_b32_e32 v0, s4
	v_cndmask_b32_e64 v8, v0, v1, s[60:61]
	v_mov_b32_e32 v0, 0x4000
	v_mov_b32_e32 v1, 0x800
	v_cndmask_b32_e64 v173, v0, v1, s[60:61]
	v_cmp_lt_i32_e32 vcc, v8, v173
	s_barrier
	s_cmp_lg_u32 s92, 0x100
	s_cbranch_scc1 .Lp5_orig
	s_load_dwordx4 s[4:7], s[70:71], 0x40
	s_load_dwordx2 s[8:9], s[70:71], 0x50
	s_add_u32 s10, s90, 0x8900000
	s_addc_u32 s11, s91, 0
	s_lshl_b32 s12, s59, 11
	s_add_u32 s12, s12, s2
	v_mov_b32_e32 v0, v192
	v_lshlrev_b32_e32 v2, 5, v0
	v_add_u32_e32 v13, 0x1000, v2
	v_lshlrev_b32_e32 v1, 4, v0
	v_lshlrev_b32_e32 v3, 3, v0
	v_xor_b32_e32 v4, 1, v0
	v_lshlrev_b32_e32 v4, 2, v4
	v_xor_b32_e32 v5, 2, v0
	v_lshlrev_b32_e32 v5, 2, v5
	v_xor_b32_e32 v6, 4, v0
	v_lshlrev_b32_e32 v6, 2, v6
	v_xor_b32_e32 v7, 8, v0
	v_lshlrev_b32_e32 v7, 2, v7
	v_xor_b32_e32 v8, 16, v0
	v_lshlrev_b32_e32 v8, 2, v8
	v_xor_b32_e32 v9, 32, v0
	v_lshlrev_b32_e32 v9, 2, v9
	s_lshl_b32 s13, s12, 12
	v_add_u32_e32 v10, s13, v1
	s_lshl_b32 s13, s12, 13
	v_add_u32_e32 v11, s13, v2
	s_lshl_b32 s13, s12, 8
	v_add_u32_e32 v12, s13, v3
	v_add_u32_e32 v14, 0x1000, v11
	v_mov_b32_e32 v208, 0
	v_mov_b32_e32 v209, 0
	v_mov_b32_e32 v210, 0
	v_mov_b32_e32 v211, 0
	v_mov_b32_e32 v212, 0
	v_mov_b32_e32 v213, 0
	v_mov_b32_e32 v214, 0
	v_mov_b32_e32 v215, 0
	v_mov_b32_e32 v216, 0
	v_mov_b32_e32 v217, 0
	v_mov_b32_e32 v218, 0
	v_mov_b32_e32 v219, 0
	v_mov_b32_e32 v220, 0
	v_mov_b32_e32 v221, 0
	v_mov_b32_e32 v222, 0
	v_mov_b32_e32 v223, 0
	s_mov_b32 s14, 0x3a000000
	s_mov_b32 s15, 0xf800000
	v_mov_b32_e32 v255, 0x260
	s_waitcnt lgkmcnt(0)
	global_load_dwordx4 v[16:19], v2, s[4:5]
	global_load_dwordx4 v[48:51], v2, s[6:7]
	global_load_dwordx4 v[20:23], v2, s[4:5] offset:16
	global_load_dwordx4 v[52:55], v2, s[6:7] offset:16
	global_load_dwordx4 v[24:27], v2, s[4:5] offset:2048
	global_load_dwordx4 v[56:59], v2, s[6:7] offset:2048
	global_load_dwordx4 v[28:31], v2, s[4:5] offset:2064
	global_load_dwordx4 v[60:63], v2, s[6:7] offset:2064
	global_load_dwordx4 v[32:35], v13, s[4:5]
	global_load_dwordx4 v[64:67], v13, s[6:7]
	global_load_dwordx4 v[36:39], v13, s[4:5] offset:16
	global_load_dwordx4 v[68:71], v13, s[6:7] offset:16
	global_load_dwordx4 v[40:43], v13, s[4:5] offset:2048
	global_load_dwordx4 v[72:75], v13, s[6:7] offset:2048
	global_load_dwordx4 v[44:47], v13, s[4:5] offset:2064
	global_load_dwordx4 v[76:79], v13, s[6:7] offset:2064
	s_mov_b32 exec_hi, 0
	s_nop 1
	global_load_dwordx2 v[208:209], v12, s[10:11]
	v_add_u32_e32 v12, 0x10000, v12
	global_load_dwordx2 v[210:211], v12, s[10:11]
	v_add_u32_e32 v12, 0x10000, v12
	global_load_dwordx2 v[212:213], v12, s[10:11]
	v_add_u32_e32 v12, 0x10000, v12
	global_load_dwordx2 v[214:215], v12, s[10:11]
	v_add_u32_e32 v12, 0x10000, v12
	s_mov_b64 exec, -1
	s_nop 1
	global_load_dwordx4 v[80:83], v10, s[96:97]
	global_load_dwordx4 v[84:87], v10, s[96:97] offset:1024
	global_load_dwordx4 v[88:91], v10, s[96:97] offset:2048
	global_load_dwordx4 v[92:95], v10, s[96:97] offset:3072
	v_add_u32_e32 v10, 0x100000, v10
	global_load_dwordx4 v[96:99], v10, s[96:97]
	global_load_dwordx4 v[100:103], v10, s[96:97] offset:1024
	global_load_dwordx4 v[104:107], v10, s[96:97] offset:2048
	global_load_dwordx4 v[108:111], v10, s[96:97] offset:3072
	v_add_u32_e32 v10, 0x100000, v10
	global_load_dwordx4 v[112:115], v10, s[96:97]
	global_load_dwordx4 v[116:119], v10, s[96:97] offset:1024
	global_load_dwordx4 v[120:123], v10, s[96:97] offset:2048
	global_load_dwordx4 v[124:127], v10, s[96:97] offset:3072
	v_add_u32_e32 v10, 0x100000, v10
	global_load_dwordx4 v[128:131], v10, s[96:97]
	global_load_dwordx4 v[132:135], v10, s[96:97] offset:1024
	global_load_dwordx4 v[136:139], v10, s[96:97] offset:2048
	global_load_dwordx4 v[140:143], v10, s[96:97] offset:3072
	v_add_u32_e32 v10, 0x100000, v10
	s_waitcnt vmcnt(16)
	ds_bpermute_b32 v224, v4, v208
	ds_bpermute_b32 v225, v4, v209
	ds_bpermute_b32 v226, v4, v210
	ds_bpermute_b32 v227, v4, v211
	ds_bpermute_b32 v228, v4, v212
	ds_bpermute_b32 v229, v4, v213
	ds_bpermute_b32 v230, v4, v214
	ds_bpermute_b32 v231, v4, v215
	s_waitcnt lgkmcnt(0)
	v_pk_add_f32 v[208:209], v[208:209], v[224:225]
	v_pk_add_f32 v[210:211], v[210:211], v[226:227]
	v_pk_add_f32 v[212:213], v[212:213], v[228:229]
	v_pk_add_f32 v[214:215], v[214:215], v[230:231]
	ds_bpermute_b32 v224, v5, v208
	ds_bpermute_b32 v225, v5, v209
	ds_bpermute_b32 v226, v5, v210
	ds_bpermute_b32 v227, v5, v211
	ds_bpermute_b32 v228, v5, v212
	ds_bpermute_b32 v229, v5, v213
	ds_bpermute_b32 v230, v5, v214
	ds_bpermute_b32 v231, v5, v215
	s_waitcnt lgkmcnt(0)
	v_pk_add_f32 v[208:209], v[208:209], v[224:225]
	v_pk_add_f32 v[210:211], v[210:211], v[226:227]
	v_pk_add_f32 v[212:213], v[212:213], v[228:229]
	v_pk_add_f32 v[214:215], v[214:215], v[230:231]
	ds_bpermute_b32 v224, v6, v208
	ds_bpermute_b32 v225, v6, v209
	ds_bpermute_b32 v226, v6, v210
	ds_bpermute_b32 v227, v6, v211
	ds_bpermute_b32 v228, v6, v212
	ds_bpermute_b32 v229, v6, v213
	ds_bpermute_b32 v230, v6, v214
	ds_bpermute_b32 v231, v6, v215
	s_waitcnt lgkmcnt(0)
	v_pk_add_f32 v[208:209], v[208:209], v[224:225]
	v_pk_add_f32 v[210:211], v[210:211], v[226:227]
	v_pk_add_f32 v[212:213], v[212:213], v[228:229]
	v_pk_add_f32 v[214:215], v[214:215], v[230:231]
	ds_bpermute_b32 v224, v7, v208
	ds_bpermute_b32 v225, v7, v209
	ds_bpermute_b32 v226, v7, v210
	ds_bpermute_b32 v227, v7, v211
	ds_bpermute_b32 v228, v7, v212
	ds_bpermute_b32 v229, v7, v213
	ds_bpermute_b32 v230, v7, v214
	ds_bpermute_b32 v231, v7, v215
	s_waitcnt lgkmcnt(0)
; __global__ void __launch_bounds__(512, 2) hybrid_fwd(Args a) {
;     ...
;                 for (int o = 1; o < 64; o <<= 1) { s0 += __shfl_xor(s0, o); q0 += __shfl_xor(q0, o); }
;                 const float m0 = s0 * (1.0f / D); const float r0 = 1.0f / sqrtf(fmaxf(q0 * (1.0f / D) - m0 * m0, 0.f) + LN_EPS);
	v_pk_add_f32 v[208:209], v[208:209], v[224:225]
	v_pk_add_f32 v[210:211], v[210:211], v[226:227]
	v_pk_add_f32 v[212:213], v[212:213], v[228:229]
	v_pk_add_f32 v[214:215], v[214:215], v[230:231]
	ds_bpermute_b32 v224, v8, v208
	ds_bpermute_b32 v225, v8, v209
	ds_bpermute_b32 v226, v8, v210
	ds_bpermute_b32 v227, v8, v211
	ds_bpermute_b32 v228, v8, v212
	ds_bpermute_b32 v229, v8, v213
	ds_bpermute_b32 v230, v8, v214
	ds_bpermute_b32 v231, v8, v215
	s_waitcnt lgkmcnt(0)
	v_pk_add_f32 v[208:209], v[208:209], v[224:225]
	v_pk_add_f32 v[210:211], v[210:211], v[226:227]
	v_pk_add_f32 v[212:213], v[212:213], v[228:229]
	v_pk_add_f32 v[214:215], v[214:215], v[230:231]
	ds_bpermute_b32 v224, v9, v208
	ds_bpermute_b32 v225, v9, v209
	ds_bpermute_b32 v226, v9, v210
	ds_bpermute_b32 v227, v9, v211
	ds_bpermute_b32 v228, v9, v212
	ds_bpermute_b32 v229, v9, v213
	ds_bpermute_b32 v230, v9, v214
	ds_bpermute_b32 v231, v9, v215
	s_waitcnt lgkmcnt(0)
	v_pk_add_f32 v[208:209], v[208:209], v[224:225]
	v_pk_add_f32 v[210:211], v[210:211], v[226:227]
	v_pk_add_f32 v[212:213], v[212:213], v[228:229]
	v_pk_add_f32 v[214:215], v[214:215], v[230:231]
	v_pk_mul_f32 v[208:209], v[208:209], s[14:15] op_sel_hi:[1,0]
	s_nop 0
	v_fma_f32 v209, -v208, v208, v209
	v_max_f32_e32 v209, 0, v209
	v_add_f32_e32 v209, 0x3727c5ac, v209
	v_mul_f32_e32 v240, 0x4f800000, v209
	v_cmp_gt_f32_e32 vcc, s15, v209
	s_nop 1
	v_cndmask_b32_e32 v209, v209, v240, vcc
	v_sqrt_f32_e32 v241, v209
	s_nop 0
	v_add_u32_e32 v243, -1, v241
	v_add_u32_e32 v244, 1, v241
	v_fma_f32 v245, -v243, v241, v209
	v_fma_f32 v246, -v244, v241, v209
	v_cmp_ge_f32_e64 s[0:1], 0, v245
	s_nop 1
	v_cndmask_b32_e64 v243, v241, v243, s[0:1]
	v_cmp_lt_f32_e64 s[0:1], 0, v246
	s_nop 1
	v_cndmask_b32_e64 v243, v243, v244, s[0:1]
	v_mul_f32_e32 v244, 0x37800000, v243
	v_cndmask_b32_e32 v243, v243, v244, vcc
	v_cmp_class_f32_e32 vcc, v209, v255
	s_nop 1
	v_cndmask_b32_e32 v209, v243, v209, vcc
	v_div_scale_f32 v243, s[0:1], v209, v209, 1.0
	v_rcp_f32_e32 v244, v243
	v_div_scale_f32 v245, vcc, 1.0, v209, 1.0
	v_fma_f32 v246, -v243, v244, 1.0
	v_fmac_f32_e32 v244, v246, v244
	v_mul_f32_e32 v246, v245, v244
	v_fma_f32 v247, -v243, v246, v245
	v_fmac_f32_e32 v246, v247, v244
	v_fma_f32 v243, -v243, v246, v245
	v_div_fmas_f32 v243, v243, v244, v246
	v_div_fixup_f32 v209, v243, v209, 1.0
	v_pk_mul_f32 v[210:211], v[210:211], s[14:15] op_sel_hi:[1,0]
	s_nop 0
	v_fma_f32 v211, -v210, v210, v211
	v_max_f32_e32 v211, 0, v211
	v_add_f32_e32 v211, 0x3727c5ac, v211
	v_mul_f32_e32 v240, 0x4f800000, v211
	v_cmp_gt_f32_e32 vcc, s15, v211
	s_nop 1
	v_cndmask_b32_e32 v211, v211, v240, vcc
	v_sqrt_f32_e32 v241, v211
	s_nop 0
	v_add_u32_e32 v243, -1, v241
	v_add_u32_e32 v244, 1, v241
	v_fma_f32 v245, -v243, v241, v211
	v_fma_f32 v246, -v244, v241, v211
	v_cmp_ge_f32_e64 s[0:1], 0, v245
	s_nop 1
	v_cndmask_b32_e64 v243, v241, v243, s[0:1]
	v_cmp_lt_f32_e64 s[0:1], 0, v246
	s_nop 1
	v_cndmask_b32_e64 v243, v243, v244, s[0:1]
	v_mul_f32_e32 v244, 0x37800000, v243
	v_cndmask_b32_e32 v243, v243, v244, vcc
	v_cmp_class_f32_e32 vcc, v211, v255
	s_nop 1
	v_cndmask_b32_e32 v211, v243, v211, vcc
	v_div_scale_f32 v243, s[0:1], v211, v211, 1.0
	v_rcp_f32_e32 v244, v243
	v_div_scale_f32 v245, vcc, 1.0, v211, 1.0
	v_fma_f32 v246, -v243, v244, 1.0
	v_fmac_f32_e32 v244, v246, v244
	v_mul_f32_e32 v246, v245, v244
	v_fma_f32 v247, -v243, v246, v245
	v_fmac_f32_e32 v246, v247, v244
	v_fma_f32 v243, -v243, v246, v245
	v_div_fmas_f32 v243, v243, v244, v246
	v_div_fixup_f32 v211, v243, v211, 1.0
	v_pk_mul_f32 v[212:213], v[212:213], s[14:15] op_sel_hi:[1,0]
	s_nop 0
	v_fma_f32 v213, -v212, v212, v213
	v_max_f32_e32 v213, 0, v213
	v_add_f32_e32 v213, 0x3727c5ac, v213
	v_mul_f32_e32 v240, 0x4f800000, v213
	v_cmp_gt_f32_e32 vcc, s15, v213
	s_nop 1
	v_cndmask_b32_e32 v213, v213, v240, vcc
	v_sqrt_f32_e32 v241, v213
	s_nop 0
	v_add_u32_e32 v243, -1, v241
	v_add_u32_e32 v244, 1, v241
	v_fma_f32 v245, -v243, v241, v213
	v_fma_f32 v246, -v244, v241, v213
	v_cmp_ge_f32_e64 s[0:1], 0, v245
	s_nop 1
	v_cndmask_b32_e64 v243, v241, v243, s[0:1]
	v_cmp_lt_f32_e64 s[0:1], 0, v246
	s_nop 1
	v_cndmask_b32_e64 v243, v243, v244, s[0:1]
	v_mul_f32_e32 v244, 0x37800000, v243
	v_cndmask_b32_e32 v243, v243, v244, vcc
	v_cmp_class_f32_e32 vcc, v213, v255
	s_nop 1
	v_cndmask_b32_e32 v213, v243, v213, vcc
	v_div_scale_f32 v243, s[0:1], v213, v213, 1.0
	v_rcp_f32_e32 v244, v243
	v_div_scale_f32 v245, vcc, 1.0, v213, 1.0
	v_fma_f32 v246, -v243, v244, 1.0
	v_fmac_f32_e32 v244, v246, v244
	v_mul_f32_e32 v246, v245, v244
	v_fma_f32 v247, -v243, v246, v245
	v_fmac_f32_e32 v246, v247, v244
	v_fma_f32 v243, -v243, v246, v245
	v_div_fmas_f32 v243, v243, v244, v246
	v_div_fixup_f32 v213, v243, v213, 1.0
	v_pk_mul_f32 v[214:215], v[214:215], s[14:15] op_sel_hi:[1,0]
	s_nop 0
	v_fma_f32 v215, -v214, v214, v215
	v_max_f32_e32 v215, 0, v215
	v_add_f32_e32 v215, 0x3727c5ac, v215
	v_mul_f32_e32 v240, 0x4f800000, v215
	v_cmp_gt_f32_e32 vcc, s15, v215
	s_nop 1
	v_cndmask_b32_e32 v215, v215, v240, vcc
	v_sqrt_f32_e32 v241, v215
	s_nop 0
	v_add_u32_e32 v243, -1, v241
	v_add_u32_e32 v244, 1, v241
	v_fma_f32 v245, -v243, v241, v215
	v_fma_f32 v246, -v244, v241, v215
	v_cmp_ge_f32_e64 s[0:1], 0, v245
	s_nop 1
	v_cndmask_b32_e64 v243, v241, v243, s[0:1]
	v_cmp_lt_f32_e64 s[0:1], 0, v246
	s_nop 1
	v_cndmask_b32_e64 v243, v243, v244, s[0:1]
	v_mul_f32_e32 v244, 0x37800000, v243
	v_cndmask_b32_e32 v243, v243, v244, vcc
	v_cmp_class_f32_e32 vcc, v215, v255
	s_nop 1
	v_cndmask_b32_e32 v215, v243, v215, vcc
	v_div_scale_f32 v243, s[0:1], v215, v215, 1.0
	v_rcp_f32_e32 v244, v243
	v_div_scale_f32 v245, vcc, 1.0, v215, 1.0
	v_fma_f32 v246, -v243, v244, 1.0
	v_fmac_f32_e32 v244, v246, v244
	v_mul_f32_e32 v246, v245, v244
	v_fma_f32 v247, -v243, v246, v245
	v_fmac_f32_e32 v246, v247, v244
	v_fma_f32 v243, -v243, v246, v245
	v_div_fmas_f32 v243, v243, v244, v246
	v_div_fixup_f32 v215, v243, v215, 1.0
	s_waitcnt vmcnt(12)
; __global__ void __launch_bounds__(512, 2) hybrid_fwd(Args a) {
;     ...
;                 if (u == 0 || tr[u] != tr[0]) { float* o0 = a.out + (size_t)tr[u] * D + 8 * lane;
; #pragma unroll
;                     for (int j = 0; j < 4; ++j) {
;                         const f32x4 a0 = (f32x4){(float)zz[u][j][0], (float)zz[u][j][1], (float)zz[u][j][2], (float)zz[u][j][3]}, a1 = (f32x4){(float)zz[u][j][4], (float)zz[u][j][5], (float)zz[u][j][6], (float)zz[u][j][7]};
;                         const f32x4 g0 = *(const f32x4*)(a.ln_g + 512 * j + 8 * lane), g1 = *(const f32x4*)(a.ln_g + 512 * j + 8 * lane + 4), b0 = *(const f32x4*)(a.ln_b + 512 * j + 8 * lane), b1 = *(const f32x4*)(a.ln_b + 512 * j + 8 * lane + 4);
;                         *(f32x4*)(o0 + 512 * j) = (a0 - m0) * r0 * g0 + b0; *(f32x4*)(o0 + 512 * j + 4) = (a1 - m0) * r0 * g1 + b1;
;                     } }
	v_cvt_f32_f16_e32 v224, v80
	v_cvt_f32_f16_sdwa v225, v80 dst_sel:DWORD dst_unused:UNUSED_PAD src0_sel:WORD_1
	v_cvt_f32_f16_e32 v226, v81
	v_cvt_f32_f16_sdwa v227, v81 dst_sel:DWORD dst_unused:UNUSED_PAD src0_sel:WORD_1
	v_cvt_f32_f16_e32 v228, v82
	v_cvt_f32_f16_sdwa v229, v82 dst_sel:DWORD dst_unused:UNUSED_PAD src0_sel:WORD_1
	v_cvt_f32_f16_e32 v230, v83
	v_cvt_f32_f16_sdwa v231, v83 dst_sel:DWORD dst_unused:UNUSED_PAD src0_sel:WORD_1
	v_sub_f32_e32 v224, v224, v208
	v_sub_f32_e32 v225, v225, v208
	v_sub_f32_e32 v226, v226, v208
	v_sub_f32_e32 v227, v227, v208
	v_sub_f32_e32 v228, v228, v208
	v_sub_f32_e32 v229, v229, v208
	v_sub_f32_e32 v230, v230, v208
	v_sub_f32_e32 v231, v231, v208
	v_pk_mul_f32 v[224:225], v[208:209], v[224:225] op_sel:[1,0] op_sel_hi:[1,1]
	v_pk_mul_f32 v[226:227], v[208:209], v[226:227] op_sel:[1,0] op_sel_hi:[1,1]
	v_pk_mul_f32 v[228:229], v[208:209], v[228:229] op_sel:[1,0] op_sel_hi:[1,1]
	v_pk_mul_f32 v[230:231], v[208:209], v[230:231] op_sel:[1,0] op_sel_hi:[1,1]
	v_pk_fma_f32 v[224:225], v[16:17], v[224:225], v[48:49]
	v_pk_fma_f32 v[226:227], v[18:19], v[226:227], v[50:51]
	v_pk_fma_f32 v[228:229], v[20:21], v[228:229], v[52:53]
	v_pk_fma_f32 v[230:231], v[22:23], v[230:231], v[54:55]
	global_store_dwordx4 v11, v[224:227], s[8:9]
	global_store_dwordx4 v11, v[228:231], s[8:9] offset:16
	v_cvt_f32_f16_e32 v232, v84
	v_cvt_f32_f16_sdwa v233, v84 dst_sel:DWORD dst_unused:UNUSED_PAD src0_sel:WORD_1
	v_cvt_f32_f16_e32 v234, v85
	v_cvt_f32_f16_sdwa v235, v85 dst_sel:DWORD dst_unused:UNUSED_PAD src0_sel:WORD_1
	v_cvt_f32_f16_e32 v236, v86
	v_cvt_f32_f16_sdwa v237, v86 dst_sel:DWORD dst_unused:UNUSED_PAD src0_sel:WORD_1
	v_cvt_f32_f16_e32 v238, v87
	v_cvt_f32_f16_sdwa v239, v87 dst_sel:DWORD dst_unused:UNUSED_PAD src0_sel:WORD_1
	v_sub_f32_e32 v232, v232, v208
	v_sub_f32_e32 v233, v233, v208
	v_sub_f32_e32 v234, v234, v208
	v_sub_f32_e32 v235, v235, v208
	v_sub_f32_e32 v236, v236, v208
	v_sub_f32_e32 v237, v237, v208
	v_sub_f32_e32 v238, v238, v208
	v_sub_f32_e32 v239, v239, v208
	v_pk_mul_f32 v[232:233], v[208:209], v[232:233] op_sel:[1,0] op_sel_hi:[1,1]
	v_pk_mul_f32 v[234:235], v[208:209], v[234:235] op_sel:[1,0] op_sel_hi:[1,1]
	v_pk_mul_f32 v[236:237], v[208:209], v[236:237] op_sel:[1,0] op_sel_hi:[1,1]
	v_pk_mul_f32 v[238:239], v[208:209], v[238:239] op_sel:[1,0] op_sel_hi:[1,1]
	v_pk_fma_f32 v[232:233], v[24:25], v[232:233], v[56:57]
	v_pk_fma_f32 v[234:235], v[26:27], v[234:235], v[58:59]
	v_pk_fma_f32 v[236:237], v[28:29], v[236:237], v[60:61]
	v_pk_fma_f32 v[238:239], v[30:31], v[238:239], v[62:63]
	global_store_dwordx4 v11, v[232:235], s[8:9] offset:2048
	global_store_dwordx4 v11, v[236:239], s[8:9] offset:2064
	v_cvt_f32_f16_e32 v224, v88
	v_cvt_f32_f16_sdwa v225, v88 dst_sel:DWORD dst_unused:UNUSED_PAD src0_sel:WORD_1
	v_cvt_f32_f16_e32 v226, v89
	v_cvt_f32_f16_sdwa v227, v89 dst_sel:DWORD dst_unused:UNUSED_PAD src0_sel:WORD_1
	v_cvt_f32_f16_e32 v228, v90
	v_cvt_f32_f16_sdwa v229, v90 dst_sel:DWORD dst_unused:UNUSED_PAD src0_sel:WORD_1
	v_cvt_f32_f16_e32 v230, v91
	v_cvt_f32_f16_sdwa v231, v91 dst_sel:DWORD dst_unused:UNUSED_PAD src0_sel:WORD_1
	v_sub_f32_e32 v224, v224, v208
	v_sub_f32_e32 v225, v225, v208
	v_sub_f32_e32 v226, v226, v208
	v_sub_f32_e32 v227, v227, v208
	v_sub_f32_e32 v228, v228, v208
	v_sub_f32_e32 v229, v229, v208
	v_sub_f32_e32 v230, v230, v208
	v_sub_f32_e32 v231, v231, v208
	v_pk_mul_f32 v[224:225], v[208:209], v[224:225] op_sel:[1,0] op_sel_hi:[1,1]
	v_pk_mul_f32 v[226:227], v[208:209], v[226:227] op_sel:[1,0] op_sel_hi:[1,1]
	v_pk_mul_f32 v[228:229], v[208:209], v[228:229] op_sel:[1,0] op_sel_hi:[1,1]
	v_pk_mul_f32 v[230:231], v[208:209], v[230:231] op_sel:[1,0] op_sel_hi:[1,1]
	v_pk_fma_f32 v[224:225], v[32:33], v[224:225], v[64:65]
	v_pk_fma_f32 v[226:227], v[34:35], v[226:227], v[66:67]
	v_pk_fma_f32 v[228:229], v[36:37], v[228:229], v[68:69]
	v_pk_fma_f32 v[230:231], v[38:39], v[230:231], v[70:71]
	global_store_dwordx4 v14, v[224:227], s[8:9]
	global_store_dwordx4 v14, v[228:231], s[8:9] offset:16
	v_cvt_f32_f16_e32 v232, v92
	v_cvt_f32_f16_sdwa v233, v92 dst_sel:DWORD dst_unused:UNUSED_PAD src0_sel:WORD_1
	v_cvt_f32_f16_e32 v234, v93
	v_cvt_f32_f16_sdwa v235, v93 dst_sel:DWORD dst_unused:UNUSED_PAD src0_sel:WORD_1
	v_cvt_f32_f16_e32 v236, v94
	v_cvt_f32_f16_sdwa v237, v94 dst_sel:DWORD dst_unused:UNUSED_PAD src0_sel:WORD_1
	v_cvt_f32_f16_e32 v238, v95
	v_cvt_f32_f16_sdwa v239, v95 dst_sel:DWORD dst_unused:UNUSED_PAD src0_sel:WORD_1
	v_sub_f32_e32 v232, v232, v208
	v_sub_f32_e32 v233, v233, v208
	v_sub_f32_e32 v234, v234, v208
	v_sub_f32_e32 v235, v235, v208
	v_sub_f32_e32 v236, v236, v208
	v_sub_f32_e32 v237, v237, v208
	v_sub_f32_e32 v238, v238, v208
	v_sub_f32_e32 v239, v239, v208
	v_pk_mul_f32 v[232:233], v[208:209], v[232:233] op_sel:[1,0] op_sel_hi:[1,1]
	v_pk_mul_f32 v[234:235], v[208:209], v[234:235] op_sel:[1,0] op_sel_hi:[1,1]
	v_pk_mul_f32 v[236:237], v[208:209], v[236:237] op_sel:[1,0] op_sel_hi:[1,1]
	v_pk_mul_f32 v[238:239], v[208:209], v[238:239] op_sel:[1,0] op_sel_hi:[1,1]
	v_pk_fma_f32 v[232:233], v[40:41], v[232:233], v[72:73]
	v_pk_fma_f32 v[234:235], v[42:43], v[234:235], v[74:75]
	v_pk_fma_f32 v[236:237], v[44:45], v[236:237], v[76:77]
	v_pk_fma_f32 v[238:239], v[46:47], v[238:239], v[78:79]
	global_store_dwordx4 v14, v[232:235], s[8:9] offset:2048
	global_store_dwordx4 v14, v[236:239], s[8:9] offset:2064
	v_add_u32_e32 v11, 0x200000, v11
	v_add_u32_e32 v14, 0x200000, v14
	s_waitcnt vmcnt(16)
; __global__ void __launch_bounds__(512, 2) hybrid_fwd(Args a) {
;     ...
;                 if (u == 0 || tr[u] != tr[0]) { float* o0 = a.out + (size_t)tr[u] * D + 8 * lane;
; #pragma unroll
;                     for (int j = 0; j < 4; ++j) {
;                         const f32x4 a0 = (f32x4){(float)zz[u][j][0], (float)zz[u][j][1], (float)zz[u][j][2], (float)zz[u][j][3]}, a1 = (f32x4){(float)zz[u][j][4], (float)zz[u][j][5], (float)zz[u][j][6], (float)zz[u][j][7]};
;                         const f32x4 g0 = *(const f32x4*)(a.ln_g + 512 * j + 8 * lane), g1 = *(const f32x4*)(a.ln_g + 512 * j + 8 * lane + 4), b0 = *(const f32x4*)(a.ln_b + 512 * j + 8 * lane), b1 = *(const f32x4*)(a.ln_b + 512 * j + 8 * lane + 4);
;                         *(f32x4*)(o0 + 512 * j) = (a0 - m0) * r0 * g0 + b0; *(f32x4*)(o0 + 512 * j + 4) = (a1 - m0) * r0 * g1 + b1;
;                     } }
	v_cvt_f32_f16_e32 v224, v96
	v_cvt_f32_f16_sdwa v225, v96 dst_sel:DWORD dst_unused:UNUSED_PAD src0_sel:WORD_1
	v_cvt_f32_f16_e32 v226, v97
	v_cvt_f32_f16_sdwa v227, v97 dst_sel:DWORD dst_unused:UNUSED_PAD src0_sel:WORD_1
	v_cvt_f32_f16_e32 v228, v98
	v_cvt_f32_f16_sdwa v229, v98 dst_sel:DWORD dst_unused:UNUSED_PAD src0_sel:WORD_1
	v_cvt_f32_f16_e32 v230, v99
	v_cvt_f32_f16_sdwa v231, v99 dst_sel:DWORD dst_unused:UNUSED_PAD src0_sel:WORD_1
	v_sub_f32_e32 v224, v224, v210
	v_sub_f32_e32 v225, v225, v210
	v_sub_f32_e32 v226, v226, v210
	v_sub_f32_e32 v227, v227, v210
	v_sub_f32_e32 v228, v228, v210
	v_sub_f32_e32 v229, v229, v210
	v_sub_f32_e32 v230, v230, v210
	v_sub_f32_e32 v231, v231, v210
	v_pk_mul_f32 v[224:225], v[210:211], v[224:225] op_sel:[1,0] op_sel_hi:[1,1]
	v_pk_mul_f32 v[226:227], v[210:211], v[226:227] op_sel:[1,0] op_sel_hi:[1,1]
	v_pk_mul_f32 v[228:229], v[210:211], v[228:229] op_sel:[1,0] op_sel_hi:[1,1]
	v_pk_mul_f32 v[230:231], v[210:211], v[230:231] op_sel:[1,0] op_sel_hi:[1,1]
	v_pk_fma_f32 v[224:225], v[16:17], v[224:225], v[48:49]
	v_pk_fma_f32 v[226:227], v[18:19], v[226:227], v[50:51]
	v_pk_fma_f32 v[228:229], v[20:21], v[228:229], v[52:53]
	v_pk_fma_f32 v[230:231], v[22:23], v[230:231], v[54:55]
	global_store_dwordx4 v11, v[224:227], s[8:9]
	global_store_dwordx4 v11, v[228:231], s[8:9] offset:16
	v_cvt_f32_f16_e32 v232, v100
	v_cvt_f32_f16_sdwa v233, v100 dst_sel:DWORD dst_unused:UNUSED_PAD src0_sel:WORD_1
	v_cvt_f32_f16_e32 v234, v101
	v_cvt_f32_f16_sdwa v235, v101 dst_sel:DWORD dst_unused:UNUSED_PAD src0_sel:WORD_1
	v_cvt_f32_f16_e32 v236, v102
	v_cvt_f32_f16_sdwa v237, v102 dst_sel:DWORD dst_unused:UNUSED_PAD src0_sel:WORD_1
	v_cvt_f32_f16_e32 v238, v103
	v_cvt_f32_f16_sdwa v239, v103 dst_sel:DWORD dst_unused:UNUSED_PAD src0_sel:WORD_1
	v_sub_f32_e32 v232, v232, v210
	v_sub_f32_e32 v233, v233, v210
	v_sub_f32_e32 v234, v234, v210
	v_sub_f32_e32 v235, v235, v210
	v_sub_f32_e32 v236, v236, v210
	v_sub_f32_e32 v237, v237, v210
	v_sub_f32_e32 v238, v238, v210
	v_sub_f32_e32 v239, v239, v210
	v_pk_mul_f32 v[232:233], v[210:211], v[232:233] op_sel:[1,0] op_sel_hi:[1,1]
	v_pk_mul_f32 v[234:235], v[210:211], v[234:235] op_sel:[1,0] op_sel_hi:[1,1]
	v_pk_mul_f32 v[236:237], v[210:211], v[236:237] op_sel:[1,0] op_sel_hi:[1,1]
	v_pk_mul_f32 v[238:239], v[210:211], v[238:239] op_sel:[1,0] op_sel_hi:[1,1]
	v_pk_fma_f32 v[232:233], v[24:25], v[232:233], v[56:57]
	v_pk_fma_f32 v[234:235], v[26:27], v[234:235], v[58:59]
	v_pk_fma_f32 v[236:237], v[28:29], v[236:237], v[60:61]
	v_pk_fma_f32 v[238:239], v[30:31], v[238:239], v[62:63]
	global_store_dwordx4 v11, v[232:235], s[8:9] offset:2048
	global_store_dwordx4 v11, v[236:239], s[8:9] offset:2064
	v_cvt_f32_f16_e32 v224, v104
	v_cvt_f32_f16_sdwa v225, v104 dst_sel:DWORD dst_unused:UNUSED_PAD src0_sel:WORD_1
	v_cvt_f32_f16_e32 v226, v105
	v_cvt_f32_f16_sdwa v227, v105 dst_sel:DWORD dst_unused:UNUSED_PAD src0_sel:WORD_1
	v_cvt_f32_f16_e32 v228, v106
	v_cvt_f32_f16_sdwa v229, v106 dst_sel:DWORD dst_unused:UNUSED_PAD src0_sel:WORD_1
	v_cvt_f32_f16_e32 v230, v107
	v_cvt_f32_f16_sdwa v231, v107 dst_sel:DWORD dst_unused:UNUSED_PAD src0_sel:WORD_1
	v_sub_f32_e32 v224, v224, v210
	v_sub_f32_e32 v225, v225, v210
	v_sub_f32_e32 v226, v226, v210
	v_sub_f32_e32 v227, v227, v210
	v_sub_f32_e32 v228, v228, v210
	v_sub_f32_e32 v229, v229, v210
	v_sub_f32_e32 v230, v230, v210
	v_sub_f32_e32 v231, v231, v210
	v_pk_mul_f32 v[224:225], v[210:211], v[224:225] op_sel:[1,0] op_sel_hi:[1,1]
	v_pk_mul_f32 v[226:227], v[210:211], v[226:227] op_sel:[1,0] op_sel_hi:[1,1]
	v_pk_mul_f32 v[228:229], v[210:211], v[228:229] op_sel:[1,0] op_sel_hi:[1,1]
	v_pk_mul_f32 v[230:231], v[210:211], v[230:231] op_sel:[1,0] op_sel_hi:[1,1]
	v_pk_fma_f32 v[224:225], v[32:33], v[224:225], v[64:65]
	v_pk_fma_f32 v[226:227], v[34:35], v[226:227], v[66:67]
	v_pk_fma_f32 v[228:229], v[36:37], v[228:229], v[68:69]
	v_pk_fma_f32 v[230:231], v[38:39], v[230:231], v[70:71]
	global_store_dwordx4 v14, v[224:227], s[8:9]
	global_store_dwordx4 v14, v[228:231], s[8:9] offset:16
	v_cvt_f32_f16_e32 v232, v108
	v_cvt_f32_f16_sdwa v233, v108 dst_sel:DWORD dst_unused:UNUSED_PAD src0_sel:WORD_1
	v_cvt_f32_f16_e32 v234, v109
	v_cvt_f32_f16_sdwa v235, v109 dst_sel:DWORD dst_unused:UNUSED_PAD src0_sel:WORD_1
	v_cvt_f32_f16_e32 v236, v110
	v_cvt_f32_f16_sdwa v237, v110 dst_sel:DWORD dst_unused:UNUSED_PAD src0_sel:WORD_1
	v_cvt_f32_f16_e32 v238, v111
	v_cvt_f32_f16_sdwa v239, v111 dst_sel:DWORD dst_unused:UNUSED_PAD src0_sel:WORD_1
	v_sub_f32_e32 v232, v232, v210
	v_sub_f32_e32 v233, v233, v210
	v_sub_f32_e32 v234, v234, v210
	v_sub_f32_e32 v235, v235, v210
	v_sub_f32_e32 v236, v236, v210
	v_sub_f32_e32 v237, v237, v210
	v_sub_f32_e32 v238, v238, v210
	v_sub_f32_e32 v239, v239, v210
	v_pk_mul_f32 v[232:233], v[210:211], v[232:233] op_sel:[1,0] op_sel_hi:[1,1]
	v_pk_mul_f32 v[234:235], v[210:211], v[234:235] op_sel:[1,0] op_sel_hi:[1,1]
	v_pk_mul_f32 v[236:237], v[210:211], v[236:237] op_sel:[1,0] op_sel_hi:[1,1]
	v_pk_mul_f32 v[238:239], v[210:211], v[238:239] op_sel:[1,0] op_sel_hi:[1,1]
	v_pk_fma_f32 v[232:233], v[40:41], v[232:233], v[72:73]
	v_pk_fma_f32 v[234:235], v[42:43], v[234:235], v[74:75]
	v_pk_fma_f32 v[236:237], v[44:45], v[236:237], v[76:77]
	v_pk_fma_f32 v[238:239], v[46:47], v[238:239], v[78:79]
	global_store_dwordx4 v14, v[232:235], s[8:9] offset:2048
	global_store_dwordx4 v14, v[236:239], s[8:9] offset:2064
	v_add_u32_e32 v11, 0x200000, v11
	v_add_u32_e32 v14, 0x200000, v14
	s_waitcnt vmcnt(20)
; __global__ void __launch_bounds__(512, 2) hybrid_fwd(Args a) {
;     ...
;                 if (u == 0 || tr[u] != tr[0]) { float* o0 = a.out + (size_t)tr[u] * D + 8 * lane;
; #pragma unroll
;                     for (int j = 0; j < 4; ++j) {
;                         const f32x4 a0 = (f32x4){(float)zz[u][j][0], (float)zz[u][j][1], (float)zz[u][j][2], (float)zz[u][j][3]}, a1 = (f32x4){(float)zz[u][j][4], (float)zz[u][j][5], (float)zz[u][j][6], (float)zz[u][j][7]};
;                         const f32x4 g0 = *(const f32x4*)(a.ln_g + 512 * j + 8 * lane), g1 = *(const f32x4*)(a.ln_g + 512 * j + 8 * lane + 4), b0 = *(const f32x4*)(a.ln_b + 512 * j + 8 * lane), b1 = *(const f32x4*)(a.ln_b + 512 * j + 8 * lane + 4);
;                         *(f32x4*)(o0 + 512 * j) = (a0 - m0) * r0 * g0 + b0; *(f32x4*)(o0 + 512 * j + 4) = (a1 - m0) * r0 * g1 + b1;
;                     } }
	v_cvt_f32_f16_e32 v224, v112
	v_cvt_f32_f16_sdwa v225, v112 dst_sel:DWORD dst_unused:UNUSED_PAD src0_sel:WORD_1
	v_cvt_f32_f16_e32 v226, v113
	v_cvt_f32_f16_sdwa v227, v113 dst_sel:DWORD dst_unused:UNUSED_PAD src0_sel:WORD_1
	v_cvt_f32_f16_e32 v228, v114
	v_cvt_f32_f16_sdwa v229, v114 dst_sel:DWORD dst_unused:UNUSED_PAD src0_sel:WORD_1
	v_cvt_f32_f16_e32 v230, v115
	v_cvt_f32_f16_sdwa v231, v115 dst_sel:DWORD dst_unused:UNUSED_PAD src0_sel:WORD_1
	v_sub_f32_e32 v224, v224, v212
	v_sub_f32_e32 v225, v225, v212
	v_sub_f32_e32 v226, v226, v212
	v_sub_f32_e32 v227, v227, v212
	v_sub_f32_e32 v228, v228, v212
	v_sub_f32_e32 v229, v229, v212
	v_sub_f32_e32 v230, v230, v212
	v_sub_f32_e32 v231, v231, v212
	v_pk_mul_f32 v[224:225], v[212:213], v[224:225] op_sel:[1,0] op_sel_hi:[1,1]
	v_pk_mul_f32 v[226:227], v[212:213], v[226:227] op_sel:[1,0] op_sel_hi:[1,1]
	v_pk_mul_f32 v[228:229], v[212:213], v[228:229] op_sel:[1,0] op_sel_hi:[1,1]
	v_pk_mul_f32 v[230:231], v[212:213], v[230:231] op_sel:[1,0] op_sel_hi:[1,1]
	v_pk_fma_f32 v[224:225], v[16:17], v[224:225], v[48:49]
	v_pk_fma_f32 v[226:227], v[18:19], v[226:227], v[50:51]
	v_pk_fma_f32 v[228:229], v[20:21], v[228:229], v[52:53]
	v_pk_fma_f32 v[230:231], v[22:23], v[230:231], v[54:55]
	global_store_dwordx4 v11, v[224:227], s[8:9]
	global_store_dwordx4 v11, v[228:231], s[8:9] offset:16
	v_cvt_f32_f16_e32 v232, v116
	v_cvt_f32_f16_sdwa v233, v116 dst_sel:DWORD dst_unused:UNUSED_PAD src0_sel:WORD_1
	v_cvt_f32_f16_e32 v234, v117
	v_cvt_f32_f16_sdwa v235, v117 dst_sel:DWORD dst_unused:UNUSED_PAD src0_sel:WORD_1
	v_cvt_f32_f16_e32 v236, v118
	v_cvt_f32_f16_sdwa v237, v118 dst_sel:DWORD dst_unused:UNUSED_PAD src0_sel:WORD_1
	v_cvt_f32_f16_e32 v238, v119
	v_cvt_f32_f16_sdwa v239, v119 dst_sel:DWORD dst_unused:UNUSED_PAD src0_sel:WORD_1
	v_sub_f32_e32 v232, v232, v212
	v_sub_f32_e32 v233, v233, v212
	v_sub_f32_e32 v234, v234, v212
	v_sub_f32_e32 v235, v235, v212
	v_sub_f32_e32 v236, v236, v212
	v_sub_f32_e32 v237, v237, v212
	v_sub_f32_e32 v238, v238, v212
	v_sub_f32_e32 v239, v239, v212
	v_pk_mul_f32 v[232:233], v[212:213], v[232:233] op_sel:[1,0] op_sel_hi:[1,1]
	v_pk_mul_f32 v[234:235], v[212:213], v[234:235] op_sel:[1,0] op_sel_hi:[1,1]
	v_pk_mul_f32 v[236:237], v[212:213], v[236:237] op_sel:[1,0] op_sel_hi:[1,1]
	v_pk_mul_f32 v[238:239], v[212:213], v[238:239] op_sel:[1,0] op_sel_hi:[1,1]
	v_pk_fma_f32 v[232:233], v[24:25], v[232:233], v[56:57]
	v_pk_fma_f32 v[234:235], v[26:27], v[234:235], v[58:59]
	v_pk_fma_f32 v[236:237], v[28:29], v[236:237], v[60:61]
	v_pk_fma_f32 v[238:239], v[30:31], v[238:239], v[62:63]
	global_store_dwordx4 v11, v[232:235], s[8:9] offset:2048
	global_store_dwordx4 v11, v[236:239], s[8:9] offset:2064
	v_cvt_f32_f16_e32 v224, v120
	v_cvt_f32_f16_sdwa v225, v120 dst_sel:DWORD dst_unused:UNUSED_PAD src0_sel:WORD_1
	v_cvt_f32_f16_e32 v226, v121
	v_cvt_f32_f16_sdwa v227, v121 dst_sel:DWORD dst_unused:UNUSED_PAD src0_sel:WORD_1
	v_cvt_f32_f16_e32 v228, v122
	v_cvt_f32_f16_sdwa v229, v122 dst_sel:DWORD dst_unused:UNUSED_PAD src0_sel:WORD_1
	v_cvt_f32_f16_e32 v230, v123
	v_cvt_f32_f16_sdwa v231, v123 dst_sel:DWORD dst_unused:UNUSED_PAD src0_sel:WORD_1
	v_sub_f32_e32 v224, v224, v212
	v_sub_f32_e32 v225, v225, v212
	v_sub_f32_e32 v226, v226, v212
	v_sub_f32_e32 v227, v227, v212
	v_sub_f32_e32 v228, v228, v212
	v_sub_f32_e32 v229, v229, v212
	v_sub_f32_e32 v230, v230, v212
	v_sub_f32_e32 v231, v231, v212
	v_pk_mul_f32 v[224:225], v[212:213], v[224:225] op_sel:[1,0] op_sel_hi:[1,1]
	v_pk_mul_f32 v[226:227], v[212:213], v[226:227] op_sel:[1,0] op_sel_hi:[1,1]
	v_pk_mul_f32 v[228:229], v[212:213], v[228:229] op_sel:[1,0] op_sel_hi:[1,1]
	v_pk_mul_f32 v[230:231], v[212:213], v[230:231] op_sel:[1,0] op_sel_hi:[1,1]
	v_pk_fma_f32 v[224:225], v[32:33], v[224:225], v[64:65]
	v_pk_fma_f32 v[226:227], v[34:35], v[226:227], v[66:67]
	v_pk_fma_f32 v[228:229], v[36:37], v[228:229], v[68:69]
	v_pk_fma_f32 v[230:231], v[38:39], v[230:231], v[70:71]
	global_store_dwordx4 v14, v[224:227], s[8:9]
	global_store_dwordx4 v14, v[228:231], s[8:9] offset:16
	v_cvt_f32_f16_e32 v232, v124
	v_cvt_f32_f16_sdwa v233, v124 dst_sel:DWORD dst_unused:UNUSED_PAD src0_sel:WORD_1
	v_cvt_f32_f16_e32 v234, v125
	v_cvt_f32_f16_sdwa v235, v125 dst_sel:DWORD dst_unused:UNUSED_PAD src0_sel:WORD_1
	v_cvt_f32_f16_e32 v236, v126
	v_cvt_f32_f16_sdwa v237, v126 dst_sel:DWORD dst_unused:UNUSED_PAD src0_sel:WORD_1
	v_cvt_f32_f16_e32 v238, v127
	v_cvt_f32_f16_sdwa v239, v127 dst_sel:DWORD dst_unused:UNUSED_PAD src0_sel:WORD_1
	v_sub_f32_e32 v232, v232, v212
	v_sub_f32_e32 v233, v233, v212
	v_sub_f32_e32 v234, v234, v212
	v_sub_f32_e32 v235, v235, v212
	v_sub_f32_e32 v236, v236, v212
	v_sub_f32_e32 v237, v237, v212
	v_sub_f32_e32 v238, v238, v212
	v_sub_f32_e32 v239, v239, v212
	v_pk_mul_f32 v[232:233], v[212:213], v[232:233] op_sel:[1,0] op_sel_hi:[1,1]
	v_pk_mul_f32 v[234:235], v[212:213], v[234:235] op_sel:[1,0] op_sel_hi:[1,1]
	v_pk_mul_f32 v[236:237], v[212:213], v[236:237] op_sel:[1,0] op_sel_hi:[1,1]
	v_pk_mul_f32 v[238:239], v[212:213], v[238:239] op_sel:[1,0] op_sel_hi:[1,1]
	v_pk_fma_f32 v[232:233], v[40:41], v[232:233], v[72:73]
	v_pk_fma_f32 v[234:235], v[42:43], v[234:235], v[74:75]
	v_pk_fma_f32 v[236:237], v[44:45], v[236:237], v[76:77]
	v_pk_fma_f32 v[238:239], v[46:47], v[238:239], v[78:79]
	global_store_dwordx4 v14, v[232:235], s[8:9] offset:2048
	global_store_dwordx4 v14, v[236:239], s[8:9] offset:2064
	v_add_u32_e32 v11, 0x200000, v11
	v_add_u32_e32 v14, 0x200000, v14
	s_waitcnt vmcnt(24)
; __global__ void __launch_bounds__(512, 2) hybrid_fwd(Args a) {
;     ...
;             int tr[8]; f32x2 pr[8]; h8 zz[8][4];
; #pragma unroll
;             for (int u = 0; u < 8; ++u) { tr[u] = (tl + u * NGW < row_cnt) ? row_base + tl + u * NGW : row_base + tl;
;                 pr[u] = (lane < 32) ? STATS[(size_t)tr[u] * 32 + lane] : (f32x2){0.f, 0.f};
; #pragma unroll
;                 for (int j = 0; j < 4; ++j) zz[u][j] = *(const h8*)(Z16 + (size_t)tr[u] * D + 512 * j + 8 * lane); }
;     ...
;                 if (u == 0 || tr[u] != tr[0]) { float* o0 = a.out + (size_t)tr[u] * D + 8 * lane;
; #pragma unroll
;                     for (int j = 0; j < 4; ++j) {
;                         const f32x4 a0 = (f32x4){(float)zz[u][j][0], (float)zz[u][j][1], (float)zz[u][j][2], (float)zz[u][j][3]}, a1 = (f32x4){(float)zz[u][j][4], (float)zz[u][j][5], (float)zz[u][j][6], (float)zz[u][j][7]};
;                         const f32x4 g0 = *(const f32x4*)(a.ln_g + 512 * j + 8 * lane), g1 = *(const f32x4*)(a.ln_g + 512 * j + 8 * lane + 4), b0 = *(const f32x4*)(a.ln_b + 512 * j + 8 * lane), b1 = *(const f32x4*)(a.ln_b + 512 * j + 8 * lane + 4);
;                         *(f32x4*)(o0 + 512 * j) = (a0 - m0) * r0 * g0 + b0; *(f32x4*)(o0 + 512 * j + 4) = (a1 - m0) * r0 * g1 + b1;
;                     } }
	v_cvt_f32_f16_e32 v224, v128
	v_cvt_f32_f16_sdwa v225, v128 dst_sel:DWORD dst_unused:UNUSED_PAD src0_sel:WORD_1
	v_cvt_f32_f16_e32 v226, v129
	v_cvt_f32_f16_sdwa v227, v129 dst_sel:DWORD dst_unused:UNUSED_PAD src0_sel:WORD_1
	v_cvt_f32_f16_e32 v228, v130
	v_cvt_f32_f16_sdwa v229, v130 dst_sel:DWORD dst_unused:UNUSED_PAD src0_sel:WORD_1
	v_cvt_f32_f16_e32 v230, v131
	v_cvt_f32_f16_sdwa v231, v131 dst_sel:DWORD dst_unused:UNUSED_PAD src0_sel:WORD_1
	v_sub_f32_e32 v224, v224, v214
	v_sub_f32_e32 v225, v225, v214
	v_sub_f32_e32 v226, v226, v214
	v_sub_f32_e32 v227, v227, v214
	v_sub_f32_e32 v228, v228, v214
	v_sub_f32_e32 v229, v229, v214
	v_sub_f32_e32 v230, v230, v214
	v_sub_f32_e32 v231, v231, v214
	v_pk_mul_f32 v[224:225], v[214:215], v[224:225] op_sel:[1,0] op_sel_hi:[1,1]
	v_pk_mul_f32 v[226:227], v[214:215], v[226:227] op_sel:[1,0] op_sel_hi:[1,1]
	v_pk_mul_f32 v[228:229], v[214:215], v[228:229] op_sel:[1,0] op_sel_hi:[1,1]
	v_pk_mul_f32 v[230:231], v[214:215], v[230:231] op_sel:[1,0] op_sel_hi:[1,1]
	v_pk_fma_f32 v[224:225], v[16:17], v[224:225], v[48:49]
	v_pk_fma_f32 v[226:227], v[18:19], v[226:227], v[50:51]
	v_pk_fma_f32 v[228:229], v[20:21], v[228:229], v[52:53]
	v_pk_fma_f32 v[230:231], v[22:23], v[230:231], v[54:55]
	global_store_dwordx4 v11, v[224:227], s[8:9]
	global_store_dwordx4 v11, v[228:231], s[8:9] offset:16
	v_cvt_f32_f16_e32 v232, v132
	v_cvt_f32_f16_sdwa v233, v132 dst_sel:DWORD dst_unused:UNUSED_PAD src0_sel:WORD_1
	v_cvt_f32_f16_e32 v234, v133
	v_cvt_f32_f16_sdwa v235, v133 dst_sel:DWORD dst_unused:UNUSED_PAD src0_sel:WORD_1
	v_cvt_f32_f16_e32 v236, v134
	v_cvt_f32_f16_sdwa v237, v134 dst_sel:DWORD dst_unused:UNUSED_PAD src0_sel:WORD_1
	v_cvt_f32_f16_e32 v238, v135
	v_cvt_f32_f16_sdwa v239, v135 dst_sel:DWORD dst_unused:UNUSED_PAD src0_sel:WORD_1
	v_sub_f32_e32 v232, v232, v214
	v_sub_f32_e32 v233, v233, v214
	v_sub_f32_e32 v234, v234, v214
	v_sub_f32_e32 v235, v235, v214
	v_sub_f32_e32 v236, v236, v214
	v_sub_f32_e32 v237, v237, v214
	v_sub_f32_e32 v238, v238, v214
	v_sub_f32_e32 v239, v239, v214
	v_pk_mul_f32 v[232:233], v[214:215], v[232:233] op_sel:[1,0] op_sel_hi:[1,1]
	v_pk_mul_f32 v[234:235], v[214:215], v[234:235] op_sel:[1,0] op_sel_hi:[1,1]
	v_pk_mul_f32 v[236:237], v[214:215], v[236:237] op_sel:[1,0] op_sel_hi:[1,1]
	v_pk_mul_f32 v[238:239], v[214:215], v[238:239] op_sel:[1,0] op_sel_hi:[1,1]
	v_pk_fma_f32 v[232:233], v[24:25], v[232:233], v[56:57]
	v_pk_fma_f32 v[234:235], v[26:27], v[234:235], v[58:59]
	v_pk_fma_f32 v[236:237], v[28:29], v[236:237], v[60:61]
	v_pk_fma_f32 v[238:239], v[30:31], v[238:239], v[62:63]
	global_store_dwordx4 v11, v[232:235], s[8:9] offset:2048
	global_store_dwordx4 v11, v[236:239], s[8:9] offset:2064
	v_cvt_f32_f16_e32 v224, v136
	v_cvt_f32_f16_sdwa v225, v136 dst_sel:DWORD dst_unused:UNUSED_PAD src0_sel:WORD_1
	v_cvt_f32_f16_e32 v226, v137
	v_cvt_f32_f16_sdwa v227, v137 dst_sel:DWORD dst_unused:UNUSED_PAD src0_sel:WORD_1
	v_cvt_f32_f16_e32 v228, v138
	v_cvt_f32_f16_sdwa v229, v138 dst_sel:DWORD dst_unused:UNUSED_PAD src0_sel:WORD_1
	v_cvt_f32_f16_e32 v230, v139
	v_cvt_f32_f16_sdwa v231, v139 dst_sel:DWORD dst_unused:UNUSED_PAD src0_sel:WORD_1
	v_sub_f32_e32 v224, v224, v214
	v_sub_f32_e32 v225, v225, v214
	v_sub_f32_e32 v226, v226, v214
	v_sub_f32_e32 v227, v227, v214
	v_sub_f32_e32 v228, v228, v214
	v_sub_f32_e32 v229, v229, v214
	v_sub_f32_e32 v230, v230, v214
	v_sub_f32_e32 v231, v231, v214
	v_pk_mul_f32 v[224:225], v[214:215], v[224:225] op_sel:[1,0] op_sel_hi:[1,1]
	v_pk_mul_f32 v[226:227], v[214:215], v[226:227] op_sel:[1,0] op_sel_hi:[1,1]
	v_pk_mul_f32 v[228:229], v[214:215], v[228:229] op_sel:[1,0] op_sel_hi:[1,1]
	v_pk_mul_f32 v[230:231], v[214:215], v[230:231] op_sel:[1,0] op_sel_hi:[1,1]
	v_pk_fma_f32 v[224:225], v[32:33], v[224:225], v[64:65]
	v_pk_fma_f32 v[226:227], v[34:35], v[226:227], v[66:67]
	v_pk_fma_f32 v[228:229], v[36:37], v[228:229], v[68:69]
	v_pk_fma_f32 v[230:231], v[38:39], v[230:231], v[70:71]
	global_store_dwordx4 v14, v[224:227], s[8:9]
	global_store_dwordx4 v14, v[228:231], s[8:9] offset:16
	v_cvt_f32_f16_e32 v232, v140
	v_cvt_f32_f16_sdwa v233, v140 dst_sel:DWORD dst_unused:UNUSED_PAD src0_sel:WORD_1
	v_cvt_f32_f16_e32 v234, v141
	v_cvt_f32_f16_sdwa v235, v141 dst_sel:DWORD dst_unused:UNUSED_PAD src0_sel:WORD_1
	v_cvt_f32_f16_e32 v236, v142
	v_cvt_f32_f16_sdwa v237, v142 dst_sel:DWORD dst_unused:UNUSED_PAD src0_sel:WORD_1
	v_cvt_f32_f16_e32 v238, v143
	v_cvt_f32_f16_sdwa v239, v143 dst_sel:DWORD dst_unused:UNUSED_PAD src0_sel:WORD_1
	v_sub_f32_e32 v232, v232, v214
	v_sub_f32_e32 v233, v233, v214
	v_sub_f32_e32 v234, v234, v214
	v_sub_f32_e32 v235, v235, v214
	v_sub_f32_e32 v236, v236, v214
	v_sub_f32_e32 v237, v237, v214
	v_sub_f32_e32 v238, v238, v214
	v_sub_f32_e32 v239, v239, v214
	v_pk_mul_f32 v[232:233], v[214:215], v[232:233] op_sel:[1,0] op_sel_hi:[1,1]
	v_pk_mul_f32 v[234:235], v[214:215], v[234:235] op_sel:[1,0] op_sel_hi:[1,1]
	v_pk_mul_f32 v[236:237], v[214:215], v[236:237] op_sel:[1,0] op_sel_hi:[1,1]
	v_pk_mul_f32 v[238:239], v[214:215], v[238:239] op_sel:[1,0] op_sel_hi:[1,1]
	v_pk_fma_f32 v[232:233], v[40:41], v[232:233], v[72:73]
	v_pk_fma_f32 v[234:235], v[42:43], v[234:235], v[74:75]
	v_pk_fma_f32 v[236:237], v[44:45], v[236:237], v[76:77]
	v_pk_fma_f32 v[238:239], v[46:47], v[238:239], v[78:79]
	global_store_dwordx4 v14, v[232:235], s[8:9] offset:2048
	global_store_dwordx4 v14, v[236:239], s[8:9] offset:2064
	v_add_u32_e32 v11, 0x200000, v11
	v_add_u32_e32 v14, 0x200000, v14
	s_mov_b32 exec_hi, 0
	s_nop 1
	global_load_dwordx2 v[216:217], v12, s[10:11]
	v_add_u32_e32 v12, 0x10000, v12
	global_load_dwordx2 v[218:219], v12, s[10:11]
	v_add_u32_e32 v12, 0x10000, v12
	global_load_dwordx2 v[220:221], v12, s[10:11]
	v_add_u32_e32 v12, 0x10000, v12
	global_load_dwordx2 v[222:223], v12, s[10:11]
	v_add_u32_e32 v12, 0x10000, v12
	s_mov_b64 exec, -1
	s_nop 1
	global_load_dwordx4 v[144:147], v10, s[96:97]
	global_load_dwordx4 v[148:151], v10, s[96:97] offset:1024
	global_load_dwordx4 v[152:155], v10, s[96:97] offset:2048
	global_load_dwordx4 v[156:159], v10, s[96:97] offset:3072
	v_add_u32_e32 v10, 0x100000, v10
	global_load_dwordx4 v[160:163], v10, s[96:97]
	global_load_dwordx4 v[164:167], v10, s[96:97] offset:1024
	global_load_dwordx4 v[168:171], v10, s[96:97] offset:2048
	global_load_dwordx4 v[172:175], v10, s[96:97] offset:3072
	v_add_u32_e32 v10, 0x100000, v10
	global_load_dwordx4 v[176:179], v10, s[96:97]
	global_load_dwordx4 v[180:183], v10, s[96:97] offset:1024
	global_load_dwordx4 v[184:187], v10, s[96:97] offset:2048
	global_load_dwordx4 v[188:191], v10, s[96:97] offset:3072
	v_add_u32_e32 v10, 0x100000, v10
	global_load_dwordx4 v[192:195], v10, s[96:97]
	global_load_dwordx4 v[196:199], v10, s[96:97] offset:1024
	global_load_dwordx4 v[200:203], v10, s[96:97] offset:2048
	global_load_dwordx4 v[204:207], v10, s[96:97] offset:3072
	v_add_u32_e32 v10, 0x100000, v10
	s_waitcnt vmcnt(16)
; __global__ void __launch_bounds__(512, 2) hybrid_fwd(Args a) {
;     ...
;                 for (int o = 1; o < 64; o <<= 1) { s0 += __shfl_xor(s0, o); q0 += __shfl_xor(q0, o); }
;                 const float m0 = s0 * (1.0f / D); const float r0 = 1.0f / sqrtf(fmaxf(q0 * (1.0f / D) - m0 * m0, 0.f) + LN_EPS);
	ds_bpermute_b32 v232, v4, v216
	ds_bpermute_b32 v233, v4, v217
	ds_bpermute_b32 v234, v4, v218
	ds_bpermute_b32 v235, v4, v219
	ds_bpermute_b32 v236, v4, v220
	ds_bpermute_b32 v237, v4, v221
	ds_bpermute_b32 v238, v4, v222
	ds_bpermute_b32 v239, v4, v223
	s_waitcnt lgkmcnt(0)
	v_pk_add_f32 v[216:217], v[216:217], v[232:233]
	v_pk_add_f32 v[218:219], v[218:219], v[234:235]
	v_pk_add_f32 v[220:221], v[220:221], v[236:237]
	v_pk_add_f32 v[222:223], v[222:223], v[238:239]
	ds_bpermute_b32 v232, v5, v216
	ds_bpermute_b32 v233, v5, v217
	ds_bpermute_b32 v234, v5, v218
	ds_bpermute_b32 v235, v5, v219
	ds_bpermute_b32 v236, v5, v220
	ds_bpermute_b32 v237, v5, v221
	ds_bpermute_b32 v238, v5, v222
	ds_bpermute_b32 v239, v5, v223
	s_waitcnt lgkmcnt(0)
	v_pk_add_f32 v[216:217], v[216:217], v[232:233]
	v_pk_add_f32 v[218:219], v[218:219], v[234:235]
	v_pk_add_f32 v[220:221], v[220:221], v[236:237]
	v_pk_add_f32 v[222:223], v[222:223], v[238:239]
	ds_bpermute_b32 v232, v6, v216
	ds_bpermute_b32 v233, v6, v217
	ds_bpermute_b32 v234, v6, v218
	ds_bpermute_b32 v235, v6, v219
	ds_bpermute_b32 v236, v6, v220
	ds_bpermute_b32 v237, v6, v221
	ds_bpermute_b32 v238, v6, v222
	ds_bpermute_b32 v239, v6, v223
	s_waitcnt lgkmcnt(0)
	v_pk_add_f32 v[216:217], v[216:217], v[232:233]
	v_pk_add_f32 v[218:219], v[218:219], v[234:235]
	v_pk_add_f32 v[220:221], v[220:221], v[236:237]
	v_pk_add_f32 v[222:223], v[222:223], v[238:239]
	ds_bpermute_b32 v232, v7, v216
	ds_bpermute_b32 v233, v7, v217
	ds_bpermute_b32 v234, v7, v218
	ds_bpermute_b32 v235, v7, v219
	ds_bpermute_b32 v236, v7, v220
	ds_bpermute_b32 v237, v7, v221
	ds_bpermute_b32 v238, v7, v222
	ds_bpermute_b32 v239, v7, v223
	s_waitcnt lgkmcnt(0)
	v_pk_add_f32 v[216:217], v[216:217], v[232:233]
	v_pk_add_f32 v[218:219], v[218:219], v[234:235]
	v_pk_add_f32 v[220:221], v[220:221], v[236:237]
	v_pk_add_f32 v[222:223], v[222:223], v[238:239]
	ds_bpermute_b32 v232, v8, v216
	ds_bpermute_b32 v233, v8, v217
	ds_bpermute_b32 v234, v8, v218
	ds_bpermute_b32 v235, v8, v219
	ds_bpermute_b32 v236, v8, v220
	ds_bpermute_b32 v237, v8, v221
	ds_bpermute_b32 v238, v8, v222
	ds_bpermute_b32 v239, v8, v223
	s_waitcnt lgkmcnt(0)
	v_pk_add_f32 v[216:217], v[216:217], v[232:233]
	v_pk_add_f32 v[218:219], v[218:219], v[234:235]
	v_pk_add_f32 v[220:221], v[220:221], v[236:237]
	v_pk_add_f32 v[222:223], v[222:223], v[238:239]
	ds_bpermute_b32 v232, v9, v216
	ds_bpermute_b32 v233, v9, v217
	ds_bpermute_b32 v234, v9, v218
	ds_bpermute_b32 v235, v9, v219
	ds_bpermute_b32 v236, v9, v220
	ds_bpermute_b32 v237, v9, v221
	ds_bpermute_b32 v238, v9, v222
	ds_bpermute_b32 v239, v9, v223
	s_waitcnt lgkmcnt(0)
	v_pk_add_f32 v[216:217], v[216:217], v[232:233]
	v_pk_add_f32 v[218:219], v[218:219], v[234:235]
	v_pk_add_f32 v[220:221], v[220:221], v[236:237]
	v_pk_add_f32 v[222:223], v[222:223], v[238:239]
	v_pk_mul_f32 v[216:217], v[216:217], s[14:15] op_sel_hi:[1,0]
	s_nop 0
	v_fma_f32 v217, -v216, v216, v217
	v_max_f32_e32 v217, 0, v217
	v_add_f32_e32 v217, 0x3727c5ac, v217
	v_mul_f32_e32 v240, 0x4f800000, v217
	v_cmp_gt_f32_e32 vcc, s15, v217
	s_nop 1
	v_cndmask_b32_e32 v217, v217, v240, vcc
	v_sqrt_f32_e32 v241, v217
	s_nop 0
	v_add_u32_e32 v243, -1, v241
	v_add_u32_e32 v244, 1, v241
	v_fma_f32 v245, -v243, v241, v217
	v_fma_f32 v246, -v244, v241, v217
	v_cmp_ge_f32_e64 s[0:1], 0, v245
	s_nop 1
	v_cndmask_b32_e64 v243, v241, v243, s[0:1]
	v_cmp_lt_f32_e64 s[0:1], 0, v246
	s_nop 1
	v_cndmask_b32_e64 v243, v243, v244, s[0:1]
	v_mul_f32_e32 v244, 0x37800000, v243
	v_cndmask_b32_e32 v243, v243, v244, vcc
	v_cmp_class_f32_e32 vcc, v217, v255
	s_nop 1
	v_cndmask_b32_e32 v217, v243, v217, vcc
	v_div_scale_f32 v243, s[0:1], v217, v217, 1.0
	v_rcp_f32_e32 v244, v243
	v_div_scale_f32 v245, vcc, 1.0, v217, 1.0
	v_fma_f32 v246, -v243, v244, 1.0
	v_fmac_f32_e32 v244, v246, v244
	v_mul_f32_e32 v246, v245, v244
	v_fma_f32 v247, -v243, v246, v245
	v_fmac_f32_e32 v246, v247, v244
	v_fma_f32 v243, -v243, v246, v245
	v_div_fmas_f32 v243, v243, v244, v246
	v_div_fixup_f32 v217, v243, v217, 1.0
	v_pk_mul_f32 v[218:219], v[218:219], s[14:15] op_sel_hi:[1,0]
	s_nop 0
	v_fma_f32 v219, -v218, v218, v219
	v_max_f32_e32 v219, 0, v219
	v_add_f32_e32 v219, 0x3727c5ac, v219
	v_mul_f32_e32 v240, 0x4f800000, v219
	v_cmp_gt_f32_e32 vcc, s15, v219
	s_nop 1
	v_cndmask_b32_e32 v219, v219, v240, vcc
	v_sqrt_f32_e32 v241, v219
	s_nop 0
	v_add_u32_e32 v243, -1, v241
	v_add_u32_e32 v244, 1, v241
	v_fma_f32 v245, -v243, v241, v219
	v_fma_f32 v246, -v244, v241, v219
	v_cmp_ge_f32_e64 s[0:1], 0, v245
	s_nop 1
	v_cndmask_b32_e64 v243, v241, v243, s[0:1]
	v_cmp_lt_f32_e64 s[0:1], 0, v246
	s_nop 1
	v_cndmask_b32_e64 v243, v243, v244, s[0:1]
	v_mul_f32_e32 v244, 0x37800000, v243
	v_cndmask_b32_e32 v243, v243, v244, vcc
	v_cmp_class_f32_e32 vcc, v219, v255
	s_nop 1
	v_cndmask_b32_e32 v219, v243, v219, vcc
	v_div_scale_f32 v243, s[0:1], v219, v219, 1.0
	v_rcp_f32_e32 v244, v243
	v_div_scale_f32 v245, vcc, 1.0, v219, 1.0
	v_fma_f32 v246, -v243, v244, 1.0
	v_fmac_f32_e32 v244, v246, v244
	v_mul_f32_e32 v246, v245, v244
	v_fma_f32 v247, -v243, v246, v245
	v_fmac_f32_e32 v246, v247, v244
	v_fma_f32 v243, -v243, v246, v245
	v_div_fmas_f32 v243, v243, v244, v246
	v_div_fixup_f32 v219, v243, v219, 1.0
	v_pk_mul_f32 v[220:221], v[220:221], s[14:15] op_sel_hi:[1,0]
	s_nop 0
	v_fma_f32 v221, -v220, v220, v221
	v_max_f32_e32 v221, 0, v221
	v_add_f32_e32 v221, 0x3727c5ac, v221
	v_mul_f32_e32 v240, 0x4f800000, v221
	v_cmp_gt_f32_e32 vcc, s15, v221
	s_nop 1
	v_cndmask_b32_e32 v221, v221, v240, vcc
	v_sqrt_f32_e32 v241, v221
	s_nop 0
	v_add_u32_e32 v243, -1, v241
	v_add_u32_e32 v244, 1, v241
; __global__ void __launch_bounds__(512, 2) hybrid_fwd(Args a) {
;     ...
;                 const float m0 = s0 * (1.0f / D); const float r0 = 1.0f / sqrtf(fmaxf(q0 * (1.0f / D) - m0 * m0, 0.f) + LN_EPS);
;                 if (u == 0 || tr[u] != tr[0]) { float* o0 = a.out + (size_t)tr[u] * D + 8 * lane;
; #pragma unroll
;                     for (int j = 0; j < 4; ++j) {
;                         const f32x4 a0 = (f32x4){(float)zz[u][j][0], (float)zz[u][j][1], (float)zz[u][j][2], (float)zz[u][j][3]}, a1 = (f32x4){(float)zz[u][j][4], (float)zz[u][j][5], (float)zz[u][j][6], (float)zz[u][j][7]};
;                         const f32x4 g0 = *(const f32x4*)(a.ln_g + 512 * j + 8 * lane), g1 = *(const f32x4*)(a.ln_g + 512 * j + 8 * lane + 4), b0 = *(const f32x4*)(a.ln_b + 512 * j + 8 * lane), b1 = *(const f32x4*)(a.ln_b + 512 * j + 8 * lane + 4);
;                         *(f32x4*)(o0 + 512 * j) = (a0 - m0) * r0 * g0 + b0; *(f32x4*)(o0 + 512 * j + 4) = (a1 - m0) * r0 * g1 + b1;
;                     } }
	v_fma_f32 v245, -v243, v241, v221
	v_fma_f32 v246, -v244, v241, v221
	v_cmp_ge_f32_e64 s[0:1], 0, v245
	s_nop 1
	v_cndmask_b32_e64 v243, v241, v243, s[0:1]
	v_cmp_lt_f32_e64 s[0:1], 0, v246
	s_nop 1
	v_cndmask_b32_e64 v243, v243, v244, s[0:1]
	v_mul_f32_e32 v244, 0x37800000, v243
	v_cndmask_b32_e32 v243, v243, v244, vcc
	v_cmp_class_f32_e32 vcc, v221, v255
	s_nop 1
	v_cndmask_b32_e32 v221, v243, v221, vcc
	v_div_scale_f32 v243, s[0:1], v221, v221, 1.0
	v_rcp_f32_e32 v244, v243
	v_div_scale_f32 v245, vcc, 1.0, v221, 1.0
	v_fma_f32 v246, -v243, v244, 1.0
	v_fmac_f32_e32 v244, v246, v244
	v_mul_f32_e32 v246, v245, v244
	v_fma_f32 v247, -v243, v246, v245
	v_fmac_f32_e32 v246, v247, v244
	v_fma_f32 v243, -v243, v246, v245
	v_div_fmas_f32 v243, v243, v244, v246
	v_div_fixup_f32 v221, v243, v221, 1.0
	v_pk_mul_f32 v[222:223], v[222:223], s[14:15] op_sel_hi:[1,0]
	s_nop 0
	v_fma_f32 v223, -v222, v222, v223
	v_max_f32_e32 v223, 0, v223
	v_add_f32_e32 v223, 0x3727c5ac, v223
	v_mul_f32_e32 v240, 0x4f800000, v223
	v_cmp_gt_f32_e32 vcc, s15, v223
	s_nop 1
	v_cndmask_b32_e32 v223, v223, v240, vcc
	v_sqrt_f32_e32 v241, v223
	s_nop 0
	v_add_u32_e32 v243, -1, v241
	v_add_u32_e32 v244, 1, v241
	v_fma_f32 v245, -v243, v241, v223
	v_fma_f32 v246, -v244, v241, v223
	v_cmp_ge_f32_e64 s[0:1], 0, v245
	s_nop 1
	v_cndmask_b32_e64 v243, v241, v243, s[0:1]
	v_cmp_lt_f32_e64 s[0:1], 0, v246
	s_nop 1
	v_cndmask_b32_e64 v243, v243, v244, s[0:1]
	v_mul_f32_e32 v244, 0x37800000, v243
	v_cndmask_b32_e32 v243, v243, v244, vcc
	v_cmp_class_f32_e32 vcc, v223, v255
	s_nop 1
	v_cndmask_b32_e32 v223, v243, v223, vcc
	v_div_scale_f32 v243, s[0:1], v223, v223, 1.0
	v_rcp_f32_e32 v244, v243
	v_div_scale_f32 v245, vcc, 1.0, v223, 1.0
	v_fma_f32 v246, -v243, v244, 1.0
	v_fmac_f32_e32 v244, v246, v244
	v_mul_f32_e32 v246, v245, v244
	v_fma_f32 v247, -v243, v246, v245
	v_fmac_f32_e32 v246, v247, v244
	v_fma_f32 v243, -v243, v246, v245
	v_div_fmas_f32 v243, v243, v244, v246
	v_div_fixup_f32 v223, v243, v223, 1.0
	s_waitcnt vmcnt(12)
	v_cvt_f32_f16_e32 v224, v144
	v_cvt_f32_f16_sdwa v225, v144 dst_sel:DWORD dst_unused:UNUSED_PAD src0_sel:WORD_1
	v_cvt_f32_f16_e32 v226, v145
	v_cvt_f32_f16_sdwa v227, v145 dst_sel:DWORD dst_unused:UNUSED_PAD src0_sel:WORD_1
	v_cvt_f32_f16_e32 v228, v146
	v_cvt_f32_f16_sdwa v229, v146 dst_sel:DWORD dst_unused:UNUSED_PAD src0_sel:WORD_1
	v_cvt_f32_f16_e32 v230, v147
	v_cvt_f32_f16_sdwa v231, v147 dst_sel:DWORD dst_unused:UNUSED_PAD src0_sel:WORD_1
	v_sub_f32_e32 v224, v224, v216
	v_sub_f32_e32 v225, v225, v216
	v_sub_f32_e32 v226, v226, v216
	v_sub_f32_e32 v227, v227, v216
	v_sub_f32_e32 v228, v228, v216
	v_sub_f32_e32 v229, v229, v216
	v_sub_f32_e32 v230, v230, v216
	v_sub_f32_e32 v231, v231, v216
	v_pk_mul_f32 v[224:225], v[216:217], v[224:225] op_sel:[1,0] op_sel_hi:[1,1]
	v_pk_mul_f32 v[226:227], v[216:217], v[226:227] op_sel:[1,0] op_sel_hi:[1,1]
	v_pk_mul_f32 v[228:229], v[216:217], v[228:229] op_sel:[1,0] op_sel_hi:[1,1]
	v_pk_mul_f32 v[230:231], v[216:217], v[230:231] op_sel:[1,0] op_sel_hi:[1,1]
	v_pk_fma_f32 v[224:225], v[16:17], v[224:225], v[48:49]
	v_pk_fma_f32 v[226:227], v[18:19], v[226:227], v[50:51]
	v_pk_fma_f32 v[228:229], v[20:21], v[228:229], v[52:53]
	v_pk_fma_f32 v[230:231], v[22:23], v[230:231], v[54:55]
	global_store_dwordx4 v11, v[224:227], s[8:9]
	global_store_dwordx4 v11, v[228:231], s[8:9] offset:16
	v_cvt_f32_f16_e32 v232, v148
	v_cvt_f32_f16_sdwa v233, v148 dst_sel:DWORD dst_unused:UNUSED_PAD src0_sel:WORD_1
	v_cvt_f32_f16_e32 v234, v149
	v_cvt_f32_f16_sdwa v235, v149 dst_sel:DWORD dst_unused:UNUSED_PAD src0_sel:WORD_1
	v_cvt_f32_f16_e32 v236, v150
	v_cvt_f32_f16_sdwa v237, v150 dst_sel:DWORD dst_unused:UNUSED_PAD src0_sel:WORD_1
	v_cvt_f32_f16_e32 v238, v151
	v_cvt_f32_f16_sdwa v239, v151 dst_sel:DWORD dst_unused:UNUSED_PAD src0_sel:WORD_1
	v_sub_f32_e32 v232, v232, v216
	v_sub_f32_e32 v233, v233, v216
	v_sub_f32_e32 v234, v234, v216
	v_sub_f32_e32 v235, v235, v216
	v_sub_f32_e32 v236, v236, v216
	v_sub_f32_e32 v237, v237, v216
	v_sub_f32_e32 v238, v238, v216
	v_sub_f32_e32 v239, v239, v216
	v_pk_mul_f32 v[232:233], v[216:217], v[232:233] op_sel:[1,0] op_sel_hi:[1,1]
	v_pk_mul_f32 v[234:235], v[216:217], v[234:235] op_sel:[1,0] op_sel_hi:[1,1]
	v_pk_mul_f32 v[236:237], v[216:217], v[236:237] op_sel:[1,0] op_sel_hi:[1,1]
	v_pk_mul_f32 v[238:239], v[216:217], v[238:239] op_sel:[1,0] op_sel_hi:[1,1]
	v_pk_fma_f32 v[232:233], v[24:25], v[232:233], v[56:57]
	v_pk_fma_f32 v[234:235], v[26:27], v[234:235], v[58:59]
	v_pk_fma_f32 v[236:237], v[28:29], v[236:237], v[60:61]
	v_pk_fma_f32 v[238:239], v[30:31], v[238:239], v[62:63]
	global_store_dwordx4 v11, v[232:235], s[8:9] offset:2048
	global_store_dwordx4 v11, v[236:239], s[8:9] offset:2064
	v_cvt_f32_f16_e32 v224, v152
	v_cvt_f32_f16_sdwa v225, v152 dst_sel:DWORD dst_unused:UNUSED_PAD src0_sel:WORD_1
	v_cvt_f32_f16_e32 v226, v153
	v_cvt_f32_f16_sdwa v227, v153 dst_sel:DWORD dst_unused:UNUSED_PAD src0_sel:WORD_1
	v_cvt_f32_f16_e32 v228, v154
	v_cvt_f32_f16_sdwa v229, v154 dst_sel:DWORD dst_unused:UNUSED_PAD src0_sel:WORD_1
	v_cvt_f32_f16_e32 v230, v155
	v_cvt_f32_f16_sdwa v231, v155 dst_sel:DWORD dst_unused:UNUSED_PAD src0_sel:WORD_1
	v_sub_f32_e32 v224, v224, v216
	v_sub_f32_e32 v225, v225, v216
	v_sub_f32_e32 v226, v226, v216
	v_sub_f32_e32 v227, v227, v216
	v_sub_f32_e32 v228, v228, v216
	v_sub_f32_e32 v229, v229, v216
	v_sub_f32_e32 v230, v230, v216
	v_sub_f32_e32 v231, v231, v216
	v_pk_mul_f32 v[224:225], v[216:217], v[224:225] op_sel:[1,0] op_sel_hi:[1,1]
	v_pk_mul_f32 v[226:227], v[216:217], v[226:227] op_sel:[1,0] op_sel_hi:[1,1]
; __global__ void __launch_bounds__(512, 2) hybrid_fwd(Args a) {
;     ...
;                 if (u == 0 || tr[u] != tr[0]) { float* o0 = a.out + (size_t)tr[u] * D + 8 * lane;
; #pragma unroll
;                     for (int j = 0; j < 4; ++j) {
;                         const f32x4 a0 = (f32x4){(float)zz[u][j][0], (float)zz[u][j][1], (float)zz[u][j][2], (float)zz[u][j][3]}, a1 = (f32x4){(float)zz[u][j][4], (float)zz[u][j][5], (float)zz[u][j][6], (float)zz[u][j][7]};
;                         const f32x4 g0 = *(const f32x4*)(a.ln_g + 512 * j + 8 * lane), g1 = *(const f32x4*)(a.ln_g + 512 * j + 8 * lane + 4), b0 = *(const f32x4*)(a.ln_b + 512 * j + 8 * lane), b1 = *(const f32x4*)(a.ln_b + 512 * j + 8 * lane + 4);
;                         *(f32x4*)(o0 + 512 * j) = (a0 - m0) * r0 * g0 + b0; *(f32x4*)(o0 + 512 * j + 4) = (a1 - m0) * r0 * g1 + b1;
;                     } }
	v_pk_mul_f32 v[228:229], v[216:217], v[228:229] op_sel:[1,0] op_sel_hi:[1,1]
	v_pk_mul_f32 v[230:231], v[216:217], v[230:231] op_sel:[1,0] op_sel_hi:[1,1]
	v_pk_fma_f32 v[224:225], v[32:33], v[224:225], v[64:65]
	v_pk_fma_f32 v[226:227], v[34:35], v[226:227], v[66:67]
	v_pk_fma_f32 v[228:229], v[36:37], v[228:229], v[68:69]
	v_pk_fma_f32 v[230:231], v[38:39], v[230:231], v[70:71]
	global_store_dwordx4 v14, v[224:227], s[8:9]
	global_store_dwordx4 v14, v[228:231], s[8:9] offset:16
	v_cvt_f32_f16_e32 v232, v156
	v_cvt_f32_f16_sdwa v233, v156 dst_sel:DWORD dst_unused:UNUSED_PAD src0_sel:WORD_1
	v_cvt_f32_f16_e32 v234, v157
	v_cvt_f32_f16_sdwa v235, v157 dst_sel:DWORD dst_unused:UNUSED_PAD src0_sel:WORD_1
	v_cvt_f32_f16_e32 v236, v158
	v_cvt_f32_f16_sdwa v237, v158 dst_sel:DWORD dst_unused:UNUSED_PAD src0_sel:WORD_1
	v_cvt_f32_f16_e32 v238, v159
	v_cvt_f32_f16_sdwa v239, v159 dst_sel:DWORD dst_unused:UNUSED_PAD src0_sel:WORD_1
	v_sub_f32_e32 v232, v232, v216
	v_sub_f32_e32 v233, v233, v216
	v_sub_f32_e32 v234, v234, v216
	v_sub_f32_e32 v235, v235, v216
	v_sub_f32_e32 v236, v236, v216
	v_sub_f32_e32 v237, v237, v216
	v_sub_f32_e32 v238, v238, v216
	v_sub_f32_e32 v239, v239, v216
	v_pk_mul_f32 v[232:233], v[216:217], v[232:233] op_sel:[1,0] op_sel_hi:[1,1]
	v_pk_mul_f32 v[234:235], v[216:217], v[234:235] op_sel:[1,0] op_sel_hi:[1,1]
	v_pk_mul_f32 v[236:237], v[216:217], v[236:237] op_sel:[1,0] op_sel_hi:[1,1]
	v_pk_mul_f32 v[238:239], v[216:217], v[238:239] op_sel:[1,0] op_sel_hi:[1,1]
	v_pk_fma_f32 v[232:233], v[40:41], v[232:233], v[72:73]
	v_pk_fma_f32 v[234:235], v[42:43], v[234:235], v[74:75]
	v_pk_fma_f32 v[236:237], v[44:45], v[236:237], v[76:77]
	v_pk_fma_f32 v[238:239], v[46:47], v[238:239], v[78:79]
	global_store_dwordx4 v14, v[232:235], s[8:9] offset:2048
	global_store_dwordx4 v14, v[236:239], s[8:9] offset:2064
	v_add_u32_e32 v11, 0x200000, v11
	v_add_u32_e32 v14, 0x200000, v14
	s_waitcnt vmcnt(16)
	v_cvt_f32_f16_e32 v224, v160
	v_cvt_f32_f16_sdwa v225, v160 dst_sel:DWORD dst_unused:UNUSED_PAD src0_sel:WORD_1
	v_cvt_f32_f16_e32 v226, v161
	v_cvt_f32_f16_sdwa v227, v161 dst_sel:DWORD dst_unused:UNUSED_PAD src0_sel:WORD_1
	v_cvt_f32_f16_e32 v228, v162
	v_cvt_f32_f16_sdwa v229, v162 dst_sel:DWORD dst_unused:UNUSED_PAD src0_sel:WORD_1
	v_cvt_f32_f16_e32 v230, v163
	v_cvt_f32_f16_sdwa v231, v163 dst_sel:DWORD dst_unused:UNUSED_PAD src0_sel:WORD_1
	v_sub_f32_e32 v224, v224, v218
	v_sub_f32_e32 v225, v225, v218
	v_sub_f32_e32 v226, v226, v218
	v_sub_f32_e32 v227, v227, v218
	v_sub_f32_e32 v228, v228, v218
	v_sub_f32_e32 v229, v229, v218
	v_sub_f32_e32 v230, v230, v218
	v_sub_f32_e32 v231, v231, v218
	v_pk_mul_f32 v[224:225], v[218:219], v[224:225] op_sel:[1,0] op_sel_hi:[1,1]
	v_pk_mul_f32 v[226:227], v[218:219], v[226:227] op_sel:[1,0] op_sel_hi:[1,1]
	v_pk_mul_f32 v[228:229], v[218:219], v[228:229] op_sel:[1,0] op_sel_hi:[1,1]
	v_pk_mul_f32 v[230:231], v[218:219], v[230:231] op_sel:[1,0] op_sel_hi:[1,1]
	v_pk_fma_f32 v[224:225], v[16:17], v[224:225], v[48:49]
	v_pk_fma_f32 v[226:227], v[18:19], v[226:227], v[50:51]
	v_pk_fma_f32 v[228:229], v[20:21], v[228:229], v[52:53]
	v_pk_fma_f32 v[230:231], v[22:23], v[230:231], v[54:55]
	global_store_dwordx4 v11, v[224:227], s[8:9]
	global_store_dwordx4 v11, v[228:231], s[8:9] offset:16
	v_cvt_f32_f16_e32 v232, v164
	v_cvt_f32_f16_sdwa v233, v164 dst_sel:DWORD dst_unused:UNUSED_PAD src0_sel:WORD_1
	v_cvt_f32_f16_e32 v234, v165
	v_cvt_f32_f16_sdwa v235, v165 dst_sel:DWORD dst_unused:UNUSED_PAD src0_sel:WORD_1
	v_cvt_f32_f16_e32 v236, v166
	v_cvt_f32_f16_sdwa v237, v166 dst_sel:DWORD dst_unused:UNUSED_PAD src0_sel:WORD_1
	v_cvt_f32_f16_e32 v238, v167
	v_cvt_f32_f16_sdwa v239, v167 dst_sel:DWORD dst_unused:UNUSED_PAD src0_sel:WORD_1
	v_sub_f32_e32 v232, v232, v218
	v_sub_f32_e32 v233, v233, v218
	v_sub_f32_e32 v234, v234, v218
	v_sub_f32_e32 v235, v235, v218
	v_sub_f32_e32 v236, v236, v218
	v_sub_f32_e32 v237, v237, v218
	v_sub_f32_e32 v238, v238, v218
	v_sub_f32_e32 v239, v239, v218
	v_pk_mul_f32 v[232:233], v[218:219], v[232:233] op_sel:[1,0] op_sel_hi:[1,1]
	v_pk_mul_f32 v[234:235], v[218:219], v[234:235] op_sel:[1,0] op_sel_hi:[1,1]
	v_pk_mul_f32 v[236:237], v[218:219], v[236:237] op_sel:[1,0] op_sel_hi:[1,1]
	v_pk_mul_f32 v[238:239], v[218:219], v[238:239] op_sel:[1,0] op_sel_hi:[1,1]
	v_pk_fma_f32 v[232:233], v[24:25], v[232:233], v[56:57]
	v_pk_fma_f32 v[234:235], v[26:27], v[234:235], v[58:59]
	v_pk_fma_f32 v[236:237], v[28:29], v[236:237], v[60:61]
	v_pk_fma_f32 v[238:239], v[30:31], v[238:239], v[62:63]
	global_store_dwordx4 v11, v[232:235], s[8:9] offset:2048
	global_store_dwordx4 v11, v[236:239], s[8:9] offset:2064
	v_cvt_f32_f16_e32 v224, v168
	v_cvt_f32_f16_sdwa v225, v168 dst_sel:DWORD dst_unused:UNUSED_PAD src0_sel:WORD_1
	v_cvt_f32_f16_e32 v226, v169
	v_cvt_f32_f16_sdwa v227, v169 dst_sel:DWORD dst_unused:UNUSED_PAD src0_sel:WORD_1
	v_cvt_f32_f16_e32 v228, v170
	v_cvt_f32_f16_sdwa v229, v170 dst_sel:DWORD dst_unused:UNUSED_PAD src0_sel:WORD_1
	v_cvt_f32_f16_e32 v230, v171
	v_cvt_f32_f16_sdwa v231, v171 dst_sel:DWORD dst_unused:UNUSED_PAD src0_sel:WORD_1
	v_sub_f32_e32 v224, v224, v218
	v_sub_f32_e32 v225, v225, v218
	v_sub_f32_e32 v226, v226, v218
	v_sub_f32_e32 v227, v227, v218
	v_sub_f32_e32 v228, v228, v218
	v_sub_f32_e32 v229, v229, v218
	v_sub_f32_e32 v230, v230, v218
	v_sub_f32_e32 v231, v231, v218
	v_pk_mul_f32 v[224:225], v[218:219], v[224:225] op_sel:[1,0] op_sel_hi:[1,1]
	v_pk_mul_f32 v[226:227], v[218:219], v[226:227] op_sel:[1,0] op_sel_hi:[1,1]
	v_pk_mul_f32 v[228:229], v[218:219], v[228:229] op_sel:[1,0] op_sel_hi:[1,1]
	v_pk_mul_f32 v[230:231], v[218:219], v[230:231] op_sel:[1,0] op_sel_hi:[1,1]
; __global__ void __launch_bounds__(512, 2) hybrid_fwd(Args a) {
;     ...
;                 if (u == 0 || tr[u] != tr[0]) { float* o0 = a.out + (size_t)tr[u] * D + 8 * lane;
; #pragma unroll
;                     for (int j = 0; j < 4; ++j) {
;                         const f32x4 a0 = (f32x4){(float)zz[u][j][0], (float)zz[u][j][1], (float)zz[u][j][2], (float)zz[u][j][3]}, a1 = (f32x4){(float)zz[u][j][4], (float)zz[u][j][5], (float)zz[u][j][6], (float)zz[u][j][7]};
;                         const f32x4 g0 = *(const f32x4*)(a.ln_g + 512 * j + 8 * lane), g1 = *(const f32x4*)(a.ln_g + 512 * j + 8 * lane + 4), b0 = *(const f32x4*)(a.ln_b + 512 * j + 8 * lane), b1 = *(const f32x4*)(a.ln_b + 512 * j + 8 * lane + 4);
;                         *(f32x4*)(o0 + 512 * j) = (a0 - m0) * r0 * g0 + b0; *(f32x4*)(o0 + 512 * j + 4) = (a1 - m0) * r0 * g1 + b1;
;                     } }
	v_pk_fma_f32 v[224:225], v[32:33], v[224:225], v[64:65]
	v_pk_fma_f32 v[226:227], v[34:35], v[226:227], v[66:67]
	v_pk_fma_f32 v[228:229], v[36:37], v[228:229], v[68:69]
	v_pk_fma_f32 v[230:231], v[38:39], v[230:231], v[70:71]
	global_store_dwordx4 v14, v[224:227], s[8:9]
	global_store_dwordx4 v14, v[228:231], s[8:9] offset:16
	v_cvt_f32_f16_e32 v232, v172
	v_cvt_f32_f16_sdwa v233, v172 dst_sel:DWORD dst_unused:UNUSED_PAD src0_sel:WORD_1
	v_cvt_f32_f16_e32 v234, v173
	v_cvt_f32_f16_sdwa v235, v173 dst_sel:DWORD dst_unused:UNUSED_PAD src0_sel:WORD_1
	v_cvt_f32_f16_e32 v236, v174
	v_cvt_f32_f16_sdwa v237, v174 dst_sel:DWORD dst_unused:UNUSED_PAD src0_sel:WORD_1
	v_cvt_f32_f16_e32 v238, v175
	v_cvt_f32_f16_sdwa v239, v175 dst_sel:DWORD dst_unused:UNUSED_PAD src0_sel:WORD_1
	v_sub_f32_e32 v232, v232, v218
	v_sub_f32_e32 v233, v233, v218
	v_sub_f32_e32 v234, v234, v218
	v_sub_f32_e32 v235, v235, v218
	v_sub_f32_e32 v236, v236, v218
	v_sub_f32_e32 v237, v237, v218
	v_sub_f32_e32 v238, v238, v218
	v_sub_f32_e32 v239, v239, v218
	v_pk_mul_f32 v[232:233], v[218:219], v[232:233] op_sel:[1,0] op_sel_hi:[1,1]
	v_pk_mul_f32 v[234:235], v[218:219], v[234:235] op_sel:[1,0] op_sel_hi:[1,1]
	v_pk_mul_f32 v[236:237], v[218:219], v[236:237] op_sel:[1,0] op_sel_hi:[1,1]
	v_pk_mul_f32 v[238:239], v[218:219], v[238:239] op_sel:[1,0] op_sel_hi:[1,1]
	v_pk_fma_f32 v[232:233], v[40:41], v[232:233], v[72:73]
	v_pk_fma_f32 v[234:235], v[42:43], v[234:235], v[74:75]
	v_pk_fma_f32 v[236:237], v[44:45], v[236:237], v[76:77]
	v_pk_fma_f32 v[238:239], v[46:47], v[238:239], v[78:79]
	global_store_dwordx4 v14, v[232:235], s[8:9] offset:2048
	global_store_dwordx4 v14, v[236:239], s[8:9] offset:2064
	v_add_u32_e32 v11, 0x200000, v11
	v_add_u32_e32 v14, 0x200000, v14
	s_waitcnt vmcnt(20)
	v_cvt_f32_f16_e32 v224, v176
	v_cvt_f32_f16_sdwa v225, v176 dst_sel:DWORD dst_unused:UNUSED_PAD src0_sel:WORD_1
	v_cvt_f32_f16_e32 v226, v177
	v_cvt_f32_f16_sdwa v227, v177 dst_sel:DWORD dst_unused:UNUSED_PAD src0_sel:WORD_1
	v_cvt_f32_f16_e32 v228, v178
	v_cvt_f32_f16_sdwa v229, v178 dst_sel:DWORD dst_unused:UNUSED_PAD src0_sel:WORD_1
	v_cvt_f32_f16_e32 v230, v179
	v_cvt_f32_f16_sdwa v231, v179 dst_sel:DWORD dst_unused:UNUSED_PAD src0_sel:WORD_1
	v_sub_f32_e32 v224, v224, v220
	v_sub_f32_e32 v225, v225, v220
	v_sub_f32_e32 v226, v226, v220
	v_sub_f32_e32 v227, v227, v220
	v_sub_f32_e32 v228, v228, v220
	v_sub_f32_e32 v229, v229, v220
	v_sub_f32_e32 v230, v230, v220
	v_sub_f32_e32 v231, v231, v220
	v_pk_mul_f32 v[224:225], v[220:221], v[224:225] op_sel:[1,0] op_sel_hi:[1,1]
	v_pk_mul_f32 v[226:227], v[220:221], v[226:227] op_sel:[1,0] op_sel_hi:[1,1]
	v_pk_mul_f32 v[228:229], v[220:221], v[228:229] op_sel:[1,0] op_sel_hi:[1,1]
	v_pk_mul_f32 v[230:231], v[220:221], v[230:231] op_sel:[1,0] op_sel_hi:[1,1]
	v_pk_fma_f32 v[224:225], v[16:17], v[224:225], v[48:49]
	v_pk_fma_f32 v[226:227], v[18:19], v[226:227], v[50:51]
	v_pk_fma_f32 v[228:229], v[20:21], v[228:229], v[52:53]
	v_pk_fma_f32 v[230:231], v[22:23], v[230:231], v[54:55]
	global_store_dwordx4 v11, v[224:227], s[8:9]
	global_store_dwordx4 v11, v[228:231], s[8:9] offset:16
	v_cvt_f32_f16_e32 v232, v180
	v_cvt_f32_f16_sdwa v233, v180 dst_sel:DWORD dst_unused:UNUSED_PAD src0_sel:WORD_1
	v_cvt_f32_f16_e32 v234, v181
	v_cvt_f32_f16_sdwa v235, v181 dst_sel:DWORD dst_unused:UNUSED_PAD src0_sel:WORD_1
	v_cvt_f32_f16_e32 v236, v182
	v_cvt_f32_f16_sdwa v237, v182 dst_sel:DWORD dst_unused:UNUSED_PAD src0_sel:WORD_1
	v_cvt_f32_f16_e32 v238, v183
	v_cvt_f32_f16_sdwa v239, v183 dst_sel:DWORD dst_unused:UNUSED_PAD src0_sel:WORD_1
	v_sub_f32_e32 v232, v232, v220
	v_sub_f32_e32 v233, v233, v220
	v_sub_f32_e32 v234, v234, v220
	v_sub_f32_e32 v235, v235, v220
	v_sub_f32_e32 v236, v236, v220
	v_sub_f32_e32 v237, v237, v220
	v_sub_f32_e32 v238, v238, v220
	v_sub_f32_e32 v239, v239, v220
	v_pk_mul_f32 v[232:233], v[220:221], v[232:233] op_sel:[1,0] op_sel_hi:[1,1]
	v_pk_mul_f32 v[234:235], v[220:221], v[234:235] op_sel:[1,0] op_sel_hi:[1,1]
	v_pk_mul_f32 v[236:237], v[220:221], v[236:237] op_sel:[1,0] op_sel_hi:[1,1]
	v_pk_mul_f32 v[238:239], v[220:221], v[238:239] op_sel:[1,0] op_sel_hi:[1,1]
	v_pk_fma_f32 v[232:233], v[24:25], v[232:233], v[56:57]
	v_pk_fma_f32 v[234:235], v[26:27], v[234:235], v[58:59]
	v_pk_fma_f32 v[236:237], v[28:29], v[236:237], v[60:61]
	v_pk_fma_f32 v[238:239], v[30:31], v[238:239], v[62:63]
	global_store_dwordx4 v11, v[232:235], s[8:9] offset:2048
	global_store_dwordx4 v11, v[236:239], s[8:9] offset:2064
	v_cvt_f32_f16_e32 v224, v184
	v_cvt_f32_f16_sdwa v225, v184 dst_sel:DWORD dst_unused:UNUSED_PAD src0_sel:WORD_1
	v_cvt_f32_f16_e32 v226, v185
	v_cvt_f32_f16_sdwa v227, v185 dst_sel:DWORD dst_unused:UNUSED_PAD src0_sel:WORD_1
	v_cvt_f32_f16_e32 v228, v186
	v_cvt_f32_f16_sdwa v229, v186 dst_sel:DWORD dst_unused:UNUSED_PAD src0_sel:WORD_1
	v_cvt_f32_f16_e32 v230, v187
	v_cvt_f32_f16_sdwa v231, v187 dst_sel:DWORD dst_unused:UNUSED_PAD src0_sel:WORD_1
	v_sub_f32_e32 v224, v224, v220
	v_sub_f32_e32 v225, v225, v220
	v_sub_f32_e32 v226, v226, v220
	v_sub_f32_e32 v227, v227, v220
	v_sub_f32_e32 v228, v228, v220
	v_sub_f32_e32 v229, v229, v220
	v_sub_f32_e32 v230, v230, v220
	v_sub_f32_e32 v231, v231, v220
	v_pk_mul_f32 v[224:225], v[220:221], v[224:225] op_sel:[1,0] op_sel_hi:[1,1]
	v_pk_mul_f32 v[226:227], v[220:221], v[226:227] op_sel:[1,0] op_sel_hi:[1,1]
	v_pk_mul_f32 v[228:229], v[220:221], v[228:229] op_sel:[1,0] op_sel_hi:[1,1]
	v_pk_mul_f32 v[230:231], v[220:221], v[230:231] op_sel:[1,0] op_sel_hi:[1,1]
	v_pk_fma_f32 v[224:225], v[32:33], v[224:225], v[64:65]
	v_pk_fma_f32 v[226:227], v[34:35], v[226:227], v[66:67]
; __global__ void __launch_bounds__(512, 2) hybrid_fwd(Args a) {
;     ...
;                 if (u == 0 || tr[u] != tr[0]) { float* o0 = a.out + (size_t)tr[u] * D + 8 * lane;
; #pragma unroll
;                     for (int j = 0; j < 4; ++j) {
;                         const f32x4 a0 = (f32x4){(float)zz[u][j][0], (float)zz[u][j][1], (float)zz[u][j][2], (float)zz[u][j][3]}, a1 = (f32x4){(float)zz[u][j][4], (float)zz[u][j][5], (float)zz[u][j][6], (float)zz[u][j][7]};
;                         const f32x4 g0 = *(const f32x4*)(a.ln_g + 512 * j + 8 * lane), g1 = *(const f32x4*)(a.ln_g + 512 * j + 8 * lane + 4), b0 = *(const f32x4*)(a.ln_b + 512 * j + 8 * lane), b1 = *(const f32x4*)(a.ln_b + 512 * j + 8 * lane + 4);
;                         *(f32x4*)(o0 + 512 * j) = (a0 - m0) * r0 * g0 + b0; *(f32x4*)(o0 + 512 * j + 4) = (a1 - m0) * r0 * g1 + b1;
;                     } }
	v_pk_fma_f32 v[228:229], v[36:37], v[228:229], v[68:69]
	v_pk_fma_f32 v[230:231], v[38:39], v[230:231], v[70:71]
	global_store_dwordx4 v14, v[224:227], s[8:9]
	global_store_dwordx4 v14, v[228:231], s[8:9] offset:16
	v_cvt_f32_f16_e32 v232, v188
	v_cvt_f32_f16_sdwa v233, v188 dst_sel:DWORD dst_unused:UNUSED_PAD src0_sel:WORD_1
	v_cvt_f32_f16_e32 v234, v189
	v_cvt_f32_f16_sdwa v235, v189 dst_sel:DWORD dst_unused:UNUSED_PAD src0_sel:WORD_1
	v_cvt_f32_f16_e32 v236, v190
	v_cvt_f32_f16_sdwa v237, v190 dst_sel:DWORD dst_unused:UNUSED_PAD src0_sel:WORD_1
	v_cvt_f32_f16_e32 v238, v191
	v_cvt_f32_f16_sdwa v239, v191 dst_sel:DWORD dst_unused:UNUSED_PAD src0_sel:WORD_1
	v_sub_f32_e32 v232, v232, v220
	v_sub_f32_e32 v233, v233, v220
	v_sub_f32_e32 v234, v234, v220
	v_sub_f32_e32 v235, v235, v220
	v_sub_f32_e32 v236, v236, v220
	v_sub_f32_e32 v237, v237, v220
	v_sub_f32_e32 v238, v238, v220
	v_sub_f32_e32 v239, v239, v220
	v_pk_mul_f32 v[232:233], v[220:221], v[232:233] op_sel:[1,0] op_sel_hi:[1,1]
	v_pk_mul_f32 v[234:235], v[220:221], v[234:235] op_sel:[1,0] op_sel_hi:[1,1]
	v_pk_mul_f32 v[236:237], v[220:221], v[236:237] op_sel:[1,0] op_sel_hi:[1,1]
	v_pk_mul_f32 v[238:239], v[220:221], v[238:239] op_sel:[1,0] op_sel_hi:[1,1]
	v_pk_fma_f32 v[232:233], v[40:41], v[232:233], v[72:73]
	v_pk_fma_f32 v[234:235], v[42:43], v[234:235], v[74:75]
	v_pk_fma_f32 v[236:237], v[44:45], v[236:237], v[76:77]
	v_pk_fma_f32 v[238:239], v[46:47], v[238:239], v[78:79]
	global_store_dwordx4 v14, v[232:235], s[8:9] offset:2048
	global_store_dwordx4 v14, v[236:239], s[8:9] offset:2064
	v_add_u32_e32 v11, 0x200000, v11
	v_add_u32_e32 v14, 0x200000, v14
	s_waitcnt vmcnt(24)
	v_cvt_f32_f16_e32 v224, v192
	v_cvt_f32_f16_sdwa v225, v192 dst_sel:DWORD dst_unused:UNUSED_PAD src0_sel:WORD_1
	v_cvt_f32_f16_e32 v226, v193
	v_cvt_f32_f16_sdwa v227, v193 dst_sel:DWORD dst_unused:UNUSED_PAD src0_sel:WORD_1
	v_cvt_f32_f16_e32 v228, v194
	v_cvt_f32_f16_sdwa v229, v194 dst_sel:DWORD dst_unused:UNUSED_PAD src0_sel:WORD_1
	v_cvt_f32_f16_e32 v230, v195
	v_cvt_f32_f16_sdwa v231, v195 dst_sel:DWORD dst_unused:UNUSED_PAD src0_sel:WORD_1
	v_sub_f32_e32 v224, v224, v222
	v_sub_f32_e32 v225, v225, v222
	v_sub_f32_e32 v226, v226, v222
	v_sub_f32_e32 v227, v227, v222
	v_sub_f32_e32 v228, v228, v222
	v_sub_f32_e32 v229, v229, v222
	v_sub_f32_e32 v230, v230, v222
	v_sub_f32_e32 v231, v231, v222
	v_pk_mul_f32 v[224:225], v[222:223], v[224:225] op_sel:[1,0] op_sel_hi:[1,1]
	v_pk_mul_f32 v[226:227], v[222:223], v[226:227] op_sel:[1,0] op_sel_hi:[1,1]
	v_pk_mul_f32 v[228:229], v[222:223], v[228:229] op_sel:[1,0] op_sel_hi:[1,1]
	v_pk_mul_f32 v[230:231], v[222:223], v[230:231] op_sel:[1,0] op_sel_hi:[1,1]
	v_pk_fma_f32 v[224:225], v[16:17], v[224:225], v[48:49]
	v_pk_fma_f32 v[226:227], v[18:19], v[226:227], v[50:51]
	v_pk_fma_f32 v[228:229], v[20:21], v[228:229], v[52:53]
	v_pk_fma_f32 v[230:231], v[22:23], v[230:231], v[54:55]
	global_store_dwordx4 v11, v[224:227], s[8:9]
	global_store_dwordx4 v11, v[228:231], s[8:9] offset:16
	v_cvt_f32_f16_e32 v232, v196
	v_cvt_f32_f16_sdwa v233, v196 dst_sel:DWORD dst_unused:UNUSED_PAD src0_sel:WORD_1
	v_cvt_f32_f16_e32 v234, v197
	v_cvt_f32_f16_sdwa v235, v197 dst_sel:DWORD dst_unused:UNUSED_PAD src0_sel:WORD_1
	v_cvt_f32_f16_e32 v236, v198
	v_cvt_f32_f16_sdwa v237, v198 dst_sel:DWORD dst_unused:UNUSED_PAD src0_sel:WORD_1
	v_cvt_f32_f16_e32 v238, v199
	v_cvt_f32_f16_sdwa v239, v199 dst_sel:DWORD dst_unused:UNUSED_PAD src0_sel:WORD_1
	v_sub_f32_e32 v232, v232, v222
	v_sub_f32_e32 v233, v233, v222
	v_sub_f32_e32 v234, v234, v222
	v_sub_f32_e32 v235, v235, v222
	v_sub_f32_e32 v236, v236, v222
	v_sub_f32_e32 v237, v237, v222
	v_sub_f32_e32 v238, v238, v222
	v_sub_f32_e32 v239, v239, v222
	v_pk_mul_f32 v[232:233], v[222:223], v[232:233] op_sel:[1,0] op_sel_hi:[1,1]
	v_pk_mul_f32 v[234:235], v[222:223], v[234:235] op_sel:[1,0] op_sel_hi:[1,1]
	v_pk_mul_f32 v[236:237], v[222:223], v[236:237] op_sel:[1,0] op_sel_hi:[1,1]
	v_pk_mul_f32 v[238:239], v[222:223], v[238:239] op_sel:[1,0] op_sel_hi:[1,1]
	v_pk_fma_f32 v[232:233], v[24:25], v[232:233], v[56:57]
	v_pk_fma_f32 v[234:235], v[26:27], v[234:235], v[58:59]
	v_pk_fma_f32 v[236:237], v[28:29], v[236:237], v[60:61]
	v_pk_fma_f32 v[238:239], v[30:31], v[238:239], v[62:63]
	global_store_dwordx4 v11, v[232:235], s[8:9] offset:2048
	global_store_dwordx4 v11, v[236:239], s[8:9] offset:2064
	v_cvt_f32_f16_e32 v224, v200
	v_cvt_f32_f16_sdwa v225, v200 dst_sel:DWORD dst_unused:UNUSED_PAD src0_sel:WORD_1
	v_cvt_f32_f16_e32 v226, v201
	v_cvt_f32_f16_sdwa v227, v201 dst_sel:DWORD dst_unused:UNUSED_PAD src0_sel:WORD_1
	v_cvt_f32_f16_e32 v228, v202
; __global__ void __launch_bounds__(512, 2) hybrid_fwd(Args a) {
;     ...
;         const int xcd = bx & 7, cu_in_x = bx >> 3, per_x = G >> 3;
;         const int gw = (G % 8 == 0) ? (cu_in_x * 8 + wave) : (bx * 8 + wave), NGW = (G % 8 == 0) ? per_x * 8 : G * 8;
;         const int row_base = (G % 8 == 0) ? xcd * (M / 8) : 0, row_cnt = (G % 8 == 0) ? (M / 8) : M;
;         typedef _Float16 h8 __attribute__((ext_vector_type(8)));
;         for (int tl = gw; tl < row_cnt; tl += 8 * NGW) {
;             int tr[8]; f32x2 pr[8]; h8 zz[8][4];
; #pragma unroll
;             for (int u = 0; u < 8; ++u) { tr[u] = (tl + u * NGW < row_cnt) ? row_base + tl + u * NGW : row_base + tl;
;                 pr[u] = (lane < 32) ? STATS[(size_t)tr[u] * 32 + lane] : (f32x2){0.f, 0.f};
; #pragma unroll
;                 for (int j = 0; j < 4; ++j) zz[u][j] = *(const h8*)(Z16 + (size_t)tr[u] * D + 512 * j + 8 * lane); }
; #pragma unroll
;             for (int u = 0; u < 8; ++u) {
;                 float s0 = pr[u].x, q0 = pr[u].y;
; #pragma unroll
;                 for (int o = 1; o < 64; o <<= 1) { s0 += __shfl_xor(s0, o); q0 += __shfl_xor(q0, o); }
;     ...
;                 if (u == 0 || tr[u] != tr[0]) { float* o0 = a.out + (size_t)tr[u] * D + 8 * lane;
; #pragma unroll
;                     for (int j = 0; j < 4; ++j) {
;                         const f32x4 a0 = (f32x4){(float)zz[u][j][0], (float)zz[u][j][1], (float)zz[u][j][2], (float)zz[u][j][3]}, a1 = (f32x4){(float)zz[u][j][4], (float)zz[u][j][5], (float)zz[u][j][6], (float)zz[u][j][7]};
;                         const f32x4 g0 = *(const f32x4*)(a.ln_g + 512 * j + 8 * lane), g1 = *(const f32x4*)(a.ln_g + 512 * j + 8 * lane + 4), b0 = *(const f32x4*)(a.ln_b + 512 * j + 8 * lane), b1 = *(const f32x4*)(a.ln_b + 512 * j + 8 * lane + 4);
;                         *(f32x4*)(o0 + 512 * j) = (a0 - m0) * r0 * g0 + b0; *(f32x4*)(o0 + 512 * j + 4) = (a1 - m0) * r0 * g1 + b1;
;                     } }
	v_cvt_f32_f16_sdwa v229, v202 dst_sel:DWORD dst_unused:UNUSED_PAD src0_sel:WORD_1
	v_cvt_f32_f16_e32 v230, v203
	v_cvt_f32_f16_sdwa v231, v203 dst_sel:DWORD dst_unused:UNUSED_PAD src0_sel:WORD_1
	v_sub_f32_e32 v224, v224, v222
	v_sub_f32_e32 v225, v225, v222
	v_sub_f32_e32 v226, v226, v222
	v_sub_f32_e32 v227, v227, v222
	v_sub_f32_e32 v228, v228, v222
	v_sub_f32_e32 v229, v229, v222
	v_sub_f32_e32 v230, v230, v222
	v_sub_f32_e32 v231, v231, v222
	v_pk_mul_f32 v[224:225], v[222:223], v[224:225] op_sel:[1,0] op_sel_hi:[1,1]
	v_pk_mul_f32 v[226:227], v[222:223], v[226:227] op_sel:[1,0] op_sel_hi:[1,1]
	v_pk_mul_f32 v[228:229], v[222:223], v[228:229] op_sel:[1,0] op_sel_hi:[1,1]
	v_pk_mul_f32 v[230:231], v[222:223], v[230:231] op_sel:[1,0] op_sel_hi:[1,1]
	v_pk_fma_f32 v[224:225], v[32:33], v[224:225], v[64:65]
	v_pk_fma_f32 v[226:227], v[34:35], v[226:227], v[66:67]
	v_pk_fma_f32 v[228:229], v[36:37], v[228:229], v[68:69]
	v_pk_fma_f32 v[230:231], v[38:39], v[230:231], v[70:71]
	global_store_dwordx4 v14, v[224:227], s[8:9]
	global_store_dwordx4 v14, v[228:231], s[8:9] offset:16
	v_cvt_f32_f16_e32 v232, v204
	v_cvt_f32_f16_sdwa v233, v204 dst_sel:DWORD dst_unused:UNUSED_PAD src0_sel:WORD_1
	v_cvt_f32_f16_e32 v234, v205
	v_cvt_f32_f16_sdwa v235, v205 dst_sel:DWORD dst_unused:UNUSED_PAD src0_sel:WORD_1
	v_cvt_f32_f16_e32 v236, v206
	v_cvt_f32_f16_sdwa v237, v206 dst_sel:DWORD dst_unused:UNUSED_PAD src0_sel:WORD_1
	v_cvt_f32_f16_e32 v238, v207
	v_cvt_f32_f16_sdwa v239, v207 dst_sel:DWORD dst_unused:UNUSED_PAD src0_sel:WORD_1
	v_sub_f32_e32 v232, v232, v222
	v_sub_f32_e32 v233, v233, v222
	v_sub_f32_e32 v234, v234, v222
	v_sub_f32_e32 v235, v235, v222
	v_sub_f32_e32 v236, v236, v222
	v_sub_f32_e32 v237, v237, v222
	v_sub_f32_e32 v238, v238, v222
	v_sub_f32_e32 v239, v239, v222
	v_pk_mul_f32 v[232:233], v[222:223], v[232:233] op_sel:[1,0] op_sel_hi:[1,1]
	v_pk_mul_f32 v[234:235], v[222:223], v[234:235] op_sel:[1,0] op_sel_hi:[1,1]
	v_pk_mul_f32 v[236:237], v[222:223], v[236:237] op_sel:[1,0] op_sel_hi:[1,1]
	v_pk_mul_f32 v[238:239], v[222:223], v[238:239] op_sel:[1,0] op_sel_hi:[1,1]
	v_pk_fma_f32 v[232:233], v[40:41], v[232:233], v[72:73]
	v_pk_fma_f32 v[234:235], v[42:43], v[234:235], v[74:75]
	v_pk_fma_f32 v[236:237], v[44:45], v[236:237], v[76:77]
	v_pk_fma_f32 v[238:239], v[46:47], v[238:239], v[78:79]
	global_store_dwordx4 v14, v[232:235], s[8:9] offset:2048
	global_store_dwordx4 v14, v[236:239], s[8:9] offset:2064
	v_add_u32_e32 v11, 0x200000, v11
	v_add_u32_e32 v14, 0x200000, v14
	s_endpgm
.Lp5_orig:
	v_readlane_b32 s5, v242, 2
	s_and_saveexec_b64 s[2:3], vcc
	s_cbranch_execz .LBB0_558
	v_mov_b32_e32 v0, s72
	v_mov_b32_e32 v1, s92
	s_lshl_b32 s2, s59, 11
	v_cndmask_b32_e64 v174, v0, v1, s[60:61]
	v_mov_b32_e32 v0, s2
	v_cndmask_b32_e64 v175, 0, v0, s[60:61]
	v_lshlrev_b32_e32 v0, 3, v192
	v_mov_b32_e32 v1, 0
	v_lshl_add_u64 v[126:127], s[0:1], 0, v[0:1]
	s_load_dwordx4 s[4:7], s[70:71], 0x40
	s_load_dwordx2 s[0:1], s[70:71], 0x50
	v_lshlrev_b32_e32 v2, 4, v192
	v_mov_b32_e32 v3, v1
	v_lshl_add_u64 v[124:125], s[96:97], 0, v[2:3]
	v_mbcnt_hi_u32_b32 v2, -1, v186
	v_and_b32_e32 v0, 64, v2
	v_add_u32_e32 v3, 64, v0
	v_lshlrev_b32_e32 v0, 5, v192
	s_waitcnt lgkmcnt(0)
	v_lshl_add_u64 v[128:129], s[0:1], 0, v[0:1]
	v_lshl_add_u64 v[130:131], s[4:5], 0, v[0:1]
	v_lshl_add_u64 v[132:133], s[6:7], 0, v[0:1]
	v_xor_b32_e32 v0, 1, v2
	v_cmp_lt_i32_e32 vcc, v0, v3
	s_mov_b64 s[0:1], 0x1000
	v_lshl_add_u64 v[134:135], v[130:131], 0, s[0:1]
	v_cndmask_b32_e32 v0, v2, v0, vcc
	v_lshlrev_b32_e32 v182, 2, v0
	v_xor_b32_e32 v0, 2, v2
	v_cmp_lt_i32_e32 vcc, v0, v3
	v_lshl_add_u64 v[136:137], v[132:133], 0, s[0:1]
	s_mov_b64 s[0:1], 0x1800
	v_cndmask_b32_e32 v0, v2, v0, vcc
	v_lshlrev_b32_e32 v183, 2, v0
	v_xor_b32_e32 v0, 4, v2
	v_cmp_lt_i32_e32 vcc, v0, v3
	v_cmp_gt_u32_e64 s[2:3], 32, v192
	v_lshlrev_b32_e32 v176, 1, v174
	v_cndmask_b32_e32 v0, v2, v0, vcc
	v_lshlrev_b32_e32 v184, 2, v0
	v_xor_b32_e32 v0, 8, v2
	v_cmp_lt_i32_e32 vcc, v0, v3
	v_lshl_add_u32 v177, v174, 1, v174
	v_lshlrev_b32_e32 v178, 2, v174
	v_cndmask_b32_e32 v0, v2, v0, vcc
	v_lshlrev_b32_e32 v185, 2, v0
	v_xor_b32_e32 v0, 16, v2
	v_cmp_lt_i32_e32 vcc, v0, v3
	v_lshl_add_u32 v179, v174, 2, v174
	v_mul_lo_u32 v180, v174, 6
	v_cndmask_b32_e32 v0, v2, v0, vcc
	v_lshlrev_b32_e32 v186, 2, v0
	v_xor_b32_e32 v0, 32, v2
	v_cmp_lt_i32_e32 vcc, v0, v3
	v_mul_lo_u32 v181, v174, 7
	v_lshl_add_u64 v[138:139], v[130:131], 0, s[0:1]
	v_cndmask_b32_e32 v0, v2, v0, vcc
	v_lshlrev_b32_e32 v187, 2, v0
	v_lshl_add_u64 v[140:141], v[132:133], 0, s[0:1]
	s_mov_b64 s[4:5], 0
	s_mov_b32 s6, 0x3a000000
	s_mov_b32 s7, 0xf800000
	v_mov_b32_e32 v188, 0x260
	s_movk_i32 s10, 0x1000
	s_branch .LBB0_528
